# v11 plus the remaining same-wave LDS ordering waits of the GEMM epilogues replaced by s_nop 1
# speedup vs baseline: 1.0041x; 1.0003x over previous
.LBB0_402:
	v_and_b32_e32 v80, 15, v139
	v_mov_b32_e32 v158, s53
	v_mad_u32_u24 v80, v80, s77, v158
	v_and_b32_e32 v139, -16, v139
	v_add_u32_e32 v158, v80, v139
	ds_write_b128 v158, v[68:71]
	ds_write_b128 v158, v[76:79] offset:64
	ds_write_b128 v158, v[90:93] offset:128
	ds_write_b128 v158, v[94:97] offset:192
	v_lshl_add_u32 v160, v157, 2, s53
	s_nop 1
	ds_write_b128 v158, v[64:67] offset:4352
	ds_write_b128 v158, v[72:75] offset:4416
	ds_write_b128 v158, v[82:85] offset:4480
	ds_write_b128 v158, v[86:89] offset:4544
	v_mul_lo_u32 v64, v140, s77
	v_add_u32_e32 v139, v160, v64
	s_nop 1
	ds_read_b128 v[64:67], v139
	ds_read_b128 v[74:77], v139 offset:16
	s_cmp_eq_u32 s100, 0
	s_cbranch_scc1 .Lg2_res0
	s_waitcnt vmcnt(0)
	v_lshlrev_b32_e32 v110, 16, v48
	v_and_b32_e32 v111, 0xffff0000, v48
	v_lshlrev_b32_e32 v112, 16, v49
	v_and_b32_e32 v113, 0xffff0000, v49
	v_lshlrev_b32_e32 v106, 16, v50
	v_and_b32_e32 v107, 0xffff0000, v50
	v_lshlrev_b32_e32 v108, 16, v51
	v_and_b32_e32 v109, 0xffff0000, v51
	v_lshlrev_b32_e32 v102, 16, v52
	v_and_b32_e32 v103, 0xffff0000, v52
	v_lshlrev_b32_e32 v104, 16, v53
	v_and_b32_e32 v105, 0xffff0000, v53
	v_lshlrev_b32_e32 v98, 16, v54
	v_and_b32_e32 v99, 0xffff0000, v54
	v_lshlrev_b32_e32 v100, 16, v55
	v_and_b32_e32 v101, 0xffff0000, v55
	v_lshlrev_b32_e32 v60, 16, v56
	v_and_b32_e32 v61, 0xffff0000, v56
	v_lshlrev_b32_e32 v62, 16, v57
	v_and_b32_e32 v63, 0xffff0000, v57
	v_lshlrev_b32_e32 v56, 16, v58
	v_and_b32_e32 v57, 0xffff0000, v58
	v_lshlrev_b32_e32 v58, 16, v59
	v_and_b32_e32 v59, 0xffff0000, v59
	v_lshlrev_b32_e32 v52, 16, v170
	v_and_b32_e32 v53, 0xffff0000, v170
	v_lshlrev_b32_e32 v54, 16, v171
	v_and_b32_e32 v55, 0xffff0000, v171
	v_lshlrev_b32_e32 v48, 16, v172
	v_and_b32_e32 v49, 0xffff0000, v172
	v_lshlrev_b32_e32 v50, 16, v173
	v_and_b32_e32 v51, 0xffff0000, v173

.LBB0_565:
	v_mov_b32_e32 v86, v161
	v_mov_b32_e32 v87, v162
	v_mov_b32_e32 v161, v163
	v_pk_add_f32 v[86:87], v[86:87], v[160:161]
	v_mov_b32_e32 v160, v157
	v_mov_b32_e32 v161, v158
	v_mov_b32_e32 v157, v159
	v_pk_add_f32 v[156:157], v[160:161], v[156:157]
	v_add_f32_e32 v86, v86, v87
	v_pk_add_f32 v[156:157], v[156:157], v[156:157] op_sel:[0,1] op_sel_hi:[1,0]
	v_add_f32_e32 v86, 0, v86
	v_add_f32_e32 v152, v152, v153
	v_add_f32_e32 v154, v154, v155
	v_mov_b32_e32 v87, v82
	v_mov_b32_e32 v157, v83
	v_mov_b32_e32 v153, v84
	v_mov_b32_e32 v155, v85
	v_pk_add_f32 v[82:83], v[86:87], v[156:157]
	v_pk_add_f32 v[84:85], v[152:153], v[154:155]
	v_add_f32_e32 v4, v4, v5
	v_pk_add_f32 v[82:83], v[82:83], v[84:85]
	v_mov_b32_e32 v84, v13
	v_mov_b32_e32 v85, v14
	v_mov_b32_e32 v13, v15
	v_mov_b32_e32 v14, v9
	v_mov_b32_e32 v15, v10
	v_mov_b32_e32 v9, v11
	v_pk_add_f32 v[12:13], v[84:85], v[12:13]
	v_pk_add_f32 v[8:9], v[14:15], v[8:9]
	v_add_f32_e32 v12, v12, v13
	v_pk_add_f32 v[8:9], v[8:9], v[8:9] op_sel:[0,1] op_sel_hi:[1,0]
	v_add_f32_e32 v12, 0, v12
	v_add_f32_e32 v6, v6, v7
	v_mov_b32_e32 v13, v0
	v_mov_b32_e32 v9, v1
	v_mov_b32_e32 v5, v2
	v_mov_b32_e32 v7, v3
	v_pk_add_f32 v[0:1], v[12:13], v[8:9]
	v_pk_add_f32 v[2:3], v[4:5], v[6:7]
	s_mov_b32 s0, 0x3a800000
	v_pk_add_f32 v[0:1], v[0:1], v[2:3]
	v_mov_b32_e32 v3, v82
	v_mov_b32_e32 v2, v0
	v_mov_b32_e32 v82, v1
	v_pk_add_f32 v[0:1], v[2:3], v[82:83]
	s_add_i32 s48, s56, s64
	v_pk_fma_f32 v[0:1], v[0:1], s[0:1], v[180:181] op_sel_hi:[1,0,0]
	s_ashr_i32 s49, s48, 31
	v_mul_f32_e32 v2, 0x4b800000, v1
	v_cmp_gt_f32_e32 vcc, s66, v1
	v_cmp_gt_f32_e64 s[40:41], s66, v0
	s_lshl_b64 s[18:19], s[48:49], 8
	v_cndmask_b32_e32 v1, v1, v2, vcc
	v_mul_f32_e32 v2, 0x4b800000, v0
	v_rsq_f32_e32 v1, v1
	v_cndmask_b32_e64 v0, v0, v2, s[40:41]
	v_rsq_f32_e32 v0, v0
	s_cmp_lt_u32 s51, 16
	v_mul_f32_e32 v2, 0x45800000, v1
	v_cndmask_b32_e32 v193, v1, v2, vcc
	v_mul_f32_e32 v1, 0x45800000, v0
	v_writelane_b32 v254, s18, 39
	v_mov_b32_e32 v194, v188
	s_cselect_b64 s[28:29], -1, 0
	s_add_i32 s0, s51, -16
	v_cndmask_b32_e64 v192, v0, v1, s[40:41]
	v_writelane_b32 v254, s19, 40
	s_mov_b64 s[18:19], s[88:89]
	s_lshr_b32 s0, s0, 2
	v_lshl_add_u32 v0, v194, 2, s7
	v_writelane_b32 v254, s28, 37
	s_cmp_gt_u32 s51, 15
	ds_write2st64_b32 v0, v80, v223 offset1:1
	v_writelane_b32 v254, s29, 38
	s_cselect_b64 s[28:29], -1, 0
	s_nop 1
	v_readlane_b32 s40, v252, 1
	s_and_b64 s[34:35], s[28:29], exec
	v_readlane_b32 s41, v252, 2
	v_readlane_b32 s42, v252, 3
	v_readlane_b32 s43, v252, 4
	v_and_b32_e32 v195, 15, v194
	v_ashrrev_i32_e32 v172, 4, v194
	s_cselect_b32 s17, s0, s51
	s_mov_b64 s[42:43], s[40:41]
	s_andn2_b64 vcc, exec, s[26:27]
	s_cbranch_vccnz .LBB0_577
	v_lshlrev_b32_e32 v1, 2, v172
	v_or_b32_e32 v3, 1, v1
	v_cvt_f32_i32_e32 v2, v1
	v_cvt_f32_i32_e32 v3, v3
	v_and_b32_e32 v0, -16, v194
	v_add_u32_e32 v201, s7, v0
	v_add_u32_e32 v196, s97, v0
	v_mul_f32_e32 v0, 0xbf549a78, v2
	v_mul_f32_e32 v2, 0xbf549a78, v3
	v_or_b32_e32 v3, 2, v1
	v_cvt_f32_i32_e32 v3, v3
	v_exp_f32_e32 v0, v0
	v_exp_f32_e32 v2, v2
	s_mov_b32 s67, s56
	v_mul_f32_e32 v3, 0xbf549a78, v3
	v_exp_f32_e32 v3, v3
	s_add_i32 s56, s2, s56
	s_and_b64 s[26:27], s[28:29], exec
	s_movk_i32 s0, 0x3e0
	s_cselect_b32 s59, s0, 0xe0
	s_cmp_gt_i32 s58, 1
	v_mul_f32_e32 v200, 0.15915494, v0
	v_and_b32_e32 v0, 4, v1
	s_cselect_b64 s[46:47], -1, 0
	s_cmp_gt_u32 s3, 3
	v_or_b32_e32 v4, 3, v1
	v_mul_f32_e32 v199, 0.15915494, v2
	v_mul_f32_e32 v198, 0.15915494, v3
	v_cvt_f32_ubyte0_e32 v1, v0
	v_or_b32_e32 v2, 1, v0
	v_or_b32_e32 v3, 2, v0
	v_or_b32_e32 v0, 3, v0
	s_cselect_b64 s[90:91], -1, 0
	s_cmp_gt_u32 s3, 5
	v_cvt_f32_ubyte0_e32 v0, v0
	s_cselect_b64 s[26:27], -1, 0
	s_cmp_gt_u32 s58, 8
	v_mul_f32_e32 v0, 0xbfd49a78, v0
	s_cselect_b64 s[2:3], -1, 0
	v_cvt_f32_ubyte0_e32 v2, v2
	v_cvt_f32_ubyte0_e32 v3, v3
	v_exp_f32_e32 v0, v0
	v_writelane_b32 v254, s2, 34
	s_cmp_gt_u32 s58, 12
	v_mul_f32_e32 v1, 0xbfd49a78, v1
	v_mul_f32_e32 v2, 0xbfd49a78, v2
	v_mul_f32_e32 v3, 0xbfd49a78, v3
	v_writelane_b32 v254, s3, 35
	v_cvt_f32_i32_e32 v4, v4
	s_cselect_b64 s[2:3], -1, 0
	v_exp_f32_e32 v1, v1
	v_exp_f32_e32 v2, v2
	v_exp_f32_e32 v3, v3
	v_writelane_b32 v254, s2, 44
	v_mul_f32_e32 v175, 0.15915494, v0
	v_or_b32_e32 v0, v195, v206
	v_writelane_b32 v254, s3, 45
	v_cmp_lt_i32_e64 s[2:3], 1, v172
	v_lshlrev_b32_e32 v231, 2, v0
	v_mul_f32_e32 v4, 0xbf549a78, v4
	v_writelane_b32 v254, s2, 50
	v_mul_f32_e32 v224, 0.15915494, v1
	v_mul_f32_e32 v223, 0.15915494, v2
	v_writelane_b32 v254, s3, 51
	v_mul_f32_e32 v203, 0.15915494, v3
	v_cmp_gt_u32_e64 s[2:3], 16, v194
	ds_bpermute_b32 v80, v231, v193
	ds_read_b128 v[0:3], v201
	v_exp_f32_e32 v4, v4
	v_writelane_b32 v254, s2, 46
	s_add_i32 s0, s8, 0xfffffa80
	ds_read_b128 v[12:15], v201 offset:128
	v_writelane_b32 v254, s3, 47
	s_ashr_i32 s2, s0, 6
	s_ashr_i32 s3, s2, 31
	s_lshl_b64 s[2:3], s[2:3], 2
	v_mul_f32_e32 v197, 0.15915494, v4
	s_add_u32 s0, s18, s2
	ds_read_b128 v[4:7], v201 offset:64
	s_waitcnt lgkmcnt(0)
	v_pk_fma_f32 v[10:11], v[150:151], v[80:81], v[2:3] op_sel_hi:[1,0,1]
	v_pk_fma_f32 v[8:9], v[148:149], v[80:81], v[0:1] op_sel_hi:[1,0,1]
	ds_read_b128 v[0:3], v201 offset:192
	s_addc_u32 s2, s19, s3
	s_add_u32 s8, s0, 0x280000
	s_addc_u32 s9, s2, 0
	s_and_b32 s2, s56, s59
	v_writelane_b32 v254, s8, 48
	s_lshr_b32 s0, s2, 6
	v_pk_fma_f32 v[156:157], v[144:145], v[80:81], v[4:5] op_sel_hi:[1,0,1]
	v_writelane_b32 v254, s9, 49
	v_pk_fma_f32 v[158:159], v[146:147], v[80:81], v[6:7] op_sel_hi:[1,0,1]
	v_pk_fma_f32 v[12:13], v[140:141], v[80:81], v[12:13] op_sel_hi:[1,0,1]
	v_pk_fma_f32 v[14:15], v[142:143], v[80:81], v[14:15] op_sel_hi:[1,0,1]
	s_waitcnt lgkmcnt(0)
	v_pk_fma_f32 v[152:153], v[136:137], v[80:81], v[0:1] op_sel_hi:[1,0,1]
	v_pk_fma_f32 v[154:155], v[138:139], v[80:81], v[2:3] op_sel_hi:[1,0,1]
	v_cvt_f32_ubyte0_e32 v228, s0
	v_cvt_f32_ubyte0_e32 v229, v195
	s_mov_b64 s[8:9], -1
	s_and_b64 vcc, exec, s[46:47]
	s_cbranch_vccz .LBB0_616
	s_and_b64 vcc, exec, s[90:91]
	s_cbranch_vccz .LBB0_610
	s_and_b64 vcc, exec, s[26:27]
	s_cbranch_vccz .LBB0_607
	v_readlane_b32 s34, v254, 34
	v_readlane_b32 s35, v254, 35
	s_and_b64 vcc, exec, s[34:35]
	s_cbranch_vccz .LBB0_603
	s_cmp_lt_i32 s58, 10
	s_cbranch_scc1 .LBB0_597
	s_cmp_lg_u32 s58, 10
	s_cbranch_scc0 .LBB0_594
	v_readlane_b32 s34, v254, 44
	v_readlane_b32 s35, v254, 45
	s_and_b64 vcc, exec, s[34:35]
	s_cbranch_vccz .LBB0_590
	s_cmp_gt_i32 s58, 21
	s_cbranch_scc0 .LBB0_581
	v_readlane_b32 s8, v255, 0
	v_readlane_b32 s9, v255, 1
	s_andn2_b64 vcc, exec, s[8:9]
	s_cbranch_vccnz .LBB0_580
	s_andn2_b64 vcc, exec, s[28:29]
	s_cbranch_vccnz .LBB0_578
	v_mul_f32_e32 v0, v224, v228
	v_sin_f32_e32 v5, v0
	v_mul_f32_e32 v1, v224, v229
	v_sin_f32_e32 v80, v1
	v_cos_f32_e32 v4, v1
	v_mul_f32_e32 v1, v223, v228
	v_readlane_b32 s8, v254, 50
	ds_bpermute_b32 v2, v219, v8
	v_sin_f32_e32 v7, v1
	ds_bpermute_b32 v3, v219, v9
	v_readlane_b32 s9, v254, 51
	ds_bpermute_b32 v6, v219, v156
	ds_bpermute_b32 v161, v219, v11
	v_cndmask_b32_e64 v82, -v5, v5, s[8:9]
	v_mul_f32_e32 v5, v223, v229
	v_sin_f32_e32 v84, v5
	v_cndmask_b32_e64 v83, -v7, v7, s[8:9]
	s_waitcnt lgkmcnt(0)
	v_pk_mul_f32 v[2:3], v[82:83], v[2:3]
	ds_bpermute_b32 v7, v219, v157
	v_cndmask_b32_e64 v82, -v80, v80, s[8:9]
	v_mul_f32_e32 v80, v203, v228
	v_cndmask_b32_e64 v83, -v84, v84, s[8:9]
	v_cos_f32_e32 v84, v80
	s_waitcnt lgkmcnt(0)
	v_pk_mul_f32 v[6:7], v[82:83], v[6:7]
	v_sin_f32_e32 v80, v80
	ds_bpermute_b32 v83, v219, v10
	v_mul_f32_e32 v82, v84, v10
	v_mul_f32_e32 v84, v203, v229
	v_cos_f32_e32 v85, v84
	v_sin_f32_e32 v87, v84
	v_cndmask_b32_e64 v80, -v80, v80, s[8:9]
	s_waitcnt lgkmcnt(0)
	v_mul_f32_e32 v84, v80, v83
	v_mul_f32_e32 v86, v85, v158
	v_mul_f32_e32 v85, v175, v228
	v_cndmask_b32_e64 v83, -v87, v87, s[8:9]
	v_sin_f32_e32 v87, v85
	v_cos_f32_e32 v0, v0
	v_cos_f32_e32 v1, v1
	ds_bpermute_b32 v80, v219, v158
	v_cos_f32_e32 v162, v85
	v_cndmask_b32_e64 v163, -v87, v87, s[8:9]
	v_mov_b32_e32 v160, v11
	v_pk_fma_f32 v[0:1], v[0:1], v[8:9], v[2:3]
	v_pk_mul_f32 v[160:161], v[162:163], v[160:161]
	v_mul_f32_e32 v2, v175, v229
	s_waitcnt lgkmcnt(0)
	v_mul_f32_e32 v164, v83, v80
	v_mov_b32_e32 v85, v161
	v_sin_f32_e32 v80, v2
	ds_bpermute_b32 v161, v219, v159
	v_cos_f32_e32 v162, v2
	v_cos_f32_e32 v5, v5
	v_mov_b32_e32 v83, v160
	v_cndmask_b32_e64 v163, -v80, v80, s[8:9]
	v_mov_b32_e32 v160, v159
	v_pk_add_f32 v[2:3], v[82:83], v[84:85]
	s_waitcnt lgkmcnt(0)
	v_pk_mul_f32 v[82:83], v[162:163], v[160:161]
	v_pk_fma_f32 v[4:5], v[4:5], v[156:157], v[6:7]
	v_mov_b32_e32 v87, v82
	v_mov_b32_e32 v165, v83
	v_pk_add_f32 v[6:7], v[86:87], v[164:165]
	s_branch .LBB0_579

.LBB0_635:
	v_mad_u32_u24 v80, v202, s77, v196
	ds_write_b128 v80, v[8:11]
	ds_write_b128 v80, v[12:15] offset:64
	ds_write_b128 v80, v[152:155] offset:128
	ds_write_b128 v80, v[156:159] offset:192
	v_readlane_b32 s36, v254, 37
	s_nop 1
	v_readlane_b32 s37, v254, 38
	s_mov_b32 s3, s57
	s_andn2_b64 vcc, exec, s[36:37]
	s_cbranch_vccnz .LBB0_638
	s_lshl_b64 s[36:37], s[34:35], 15
	s_lshl_b32 s0, s2, 7
	v_ashrrev_i32_e32 v87, 31, v86
	s_add_u32 s36, s0, s36
	v_lshlrev_b64 v[8:9], 7, v[86:87]
	s_addc_u32 s37, 0, s37
	v_lshlrev_b32_e32 v10, 4, v194
	v_lshl_add_u64 v[8:9], s[36:37], 0, v[8:9]
	v_and_b32_e32 v10, 0x70, v10
	v_or_b32_e32 v8, v8, v10
	v_lshl_add_u64 v[8:9], s[42:43], 0, v[8:9]
	s_mov_b64 s[36:37], 0x4000000
	v_mul_lo_u32 v11, v86, s77
	v_lshl_add_u64 v[8:9], v[8:9], 0, s[36:37]
	v_add3_u32 v10, v11, v10, s97
	s_mov_b32 s0, 0

.LBB0_641:
	v_mov_b64_e32 v[14:15], v[6:7]
	s_andn2_b64 vcc, exec, s[44:45]
	v_mov_b64_e32 v[12:13], v[4:5]
	v_mov_b64_e32 v[10:11], v[2:3]
	v_mov_b64_e32 v[8:9], v[0:1]
	s_cbranch_vccnz .LBB0_650
	s_cmp_lg_u32 s58, 13
	s_mov_b64 s[44:45], -1
	s_cbranch_scc0 .LBB0_646
	v_mul_f32_e32 v80, 0xbfb8aa3b, v152
	v_exp_f32_e32 v80, v80
	v_mul_f32_e32 v87, 0xbfb8aa3b, v153
	v_exp_f32_e32 v87, v87
	v_mul_f32_e32 v165, 0xbfb8aa3b, v155
	v_add_f32_e32 v80, 1.0, v80
	v_rcp_f32_e32 v164, v80
	v_add_f32_e32 v80, 1.0, v87
	v_mul_f32_e32 v87, 0xbfb8aa3b, v154
	v_exp_f32_e32 v87, v87
	v_exp_f32_e32 v167, v165
	v_rcp_f32_e32 v165, v80
	v_mul_f32_e32 v8, 0xbfb8aa3b, v82
	v_add_f32_e32 v80, 1.0, v87
	v_mul_f32_e32 v87, 0xbfb8aa3b, v156
	v_rcp_f32_e32 v166, v80
	v_add_f32_e32 v80, 1.0, v167
	v_exp_f32_e32 v87, v87
	v_mul_f32_e32 v167, 0xbfb8aa3b, v157
	v_exp_f32_e32 v169, v167
	v_mul_f32_e32 v9, 0xbfb8aa3b, v83
	v_mul_f32_e32 v10, 0xbfb8aa3b, v84
	v_mul_f32_e32 v11, 0xbfb8aa3b, v85
	v_rcp_f32_e32 v167, v80
	v_add_f32_e32 v80, 1.0, v87
	v_mul_f32_e32 v87, 0xbfb8aa3b, v158
	v_exp_f32_e32 v8, v8
	v_exp_f32_e32 v9, v9
	v_exp_f32_e32 v10, v10
	v_exp_f32_e32 v11, v11
	v_mul_f32_e32 v12, 0xbfb8aa3b, v160
	v_mul_f32_e32 v13, 0xbfb8aa3b, v161
	v_mul_f32_e32 v14, 0xbfb8aa3b, v162
	v_mul_f32_e32 v15, 0xbfb8aa3b, v163
	v_rcp_f32_e32 v168, v80
	v_add_f32_e32 v80, 1.0, v169
	v_exp_f32_e32 v87, v87
	v_mul_f32_e32 v169, 0xbfb8aa3b, v159
	v_exp_f32_e32 v12, v12
	v_exp_f32_e32 v13, v13
	v_exp_f32_e32 v14, v14
	v_exp_f32_e32 v15, v15
	v_exp_f32_e32 v171, v169
	v_add_f32_e32 v8, 1.0, v8
	v_add_f32_e32 v9, 1.0, v9
	v_add_f32_e32 v10, 1.0, v10
	v_add_f32_e32 v11, 1.0, v11
	v_rcp_f32_e32 v169, v80
	v_add_f32_e32 v80, 1.0, v87
	v_rcp_f32_e32 v8, v8
	v_rcp_f32_e32 v9, v9
	v_rcp_f32_e32 v10, v10
	v_rcp_f32_e32 v11, v11
	v_add_f32_e32 v12, 1.0, v12
	v_add_f32_e32 v13, 1.0, v13
	v_add_f32_e32 v14, 1.0, v14
	v_add_f32_e32 v15, 1.0, v15
	v_rcp_f32_e32 v170, v80
	v_add_f32_e32 v80, 1.0, v171
	v_rcp_f32_e32 v12, v12
	v_rcp_f32_e32 v13, v13
	v_rcp_f32_e32 v14, v14
	v_rcp_f32_e32 v15, v15
	v_rcp_f32_e32 v171, v80
	v_pk_mul_f32 v[8:9], v[82:83], v[8:9]
	v_pk_mul_f32 v[10:11], v[84:85], v[10:11]
	v_mad_u32_u24 v80, v202, s77, v196
	v_ashrrev_i32_e32 v87, 31, v86
	v_readlane_b32 s36, v254, 54
	s_lshl_b32 s0, s16, 8
	v_readlane_b32 s3, v254, 33
	v_pk_mul_f32 v[12:13], v[160:161], v[12:13]
	v_pk_mul_f32 v[14:15], v[162:163], v[14:15]
	v_pk_mul_f32 v[164:165], v[152:153], v[164:165]
	v_pk_mul_f32 v[166:167], v[154:155], v[166:167]
	v_pk_mul_f32 v[168:169], v[156:157], v[168:169]
	v_pk_mul_f32 v[170:171], v[158:159], v[170:171]
	ds_write_b128 v80, v[8:11]
	ds_write_b128 v80, v[12:15] offset:64
	ds_write_b128 v80, v[164:167] offset:128
	ds_write_b128 v80, v[168:171] offset:192
	v_lshlrev_b64 v[8:9], 11, v[86:87]
	v_readlane_b32 s37, v254, 55
	s_or_b32 s60, s3, s0
	v_and_b32_e32 v10, 7, v194
	v_lshl_add_u64 v[8:9], v[8:9], 0, s[36:37]
	s_lshl_b64 s[36:37], s[60:61], 1
	v_lshlrev_b32_e32 v80, 4, v10
	s_add_u32 s36, s18, s36
	s_nop 1
	v_lshl_add_u64 v[8:9], v[8:9], 0, v[80:81]
	s_addc_u32 s37, s19, s37
	v_lshl_add_u64 v[8:9], s[36:37], 0, v[8:9]
	s_mov_b64 s[36:37], 0x58ff200
	v_mul_lo_u32 v11, v86, s77
	v_lshlrev_b32_e32 v10, 5, v10
	v_lshl_add_u64 v[8:9], v[8:9], 0, s[36:37]
	v_add3_u32 v10, v11, v10, s50
	s_mov_b32 s0, 0
	s_mov_b64 s[36:37], 0x4000

.LBB0_654:
	s_or_b64 exec, exec, s[44:45]
	s_waitcnt lgkmcnt(0)
	ds_read_b128 v[8:11], v201 offset:256
	ds_read_b128 v[12:15], v201 offset:320
	ds_read_b128 v[164:167], v201 offset:384
	ds_read_b128 v[168:171], v201 offset:448
	s_lshl_b32 s0, s16, 8
	v_readlane_b32 s3, v254, 33
	s_waitcnt lgkmcnt(0)
	v_pk_mul_f32 v[10:11], v[84:85], v[10:11]
	v_pk_mul_f32 v[8:9], v[82:83], v[8:9]
	v_mad_u32_u24 v80, v202, s77, v196
	v_ashrrev_i32_e32 v87, 31, v86
	s_or_b32 s60, s3, s0
	v_pk_mul_f32 v[14:15], v[162:163], v[14:15]
	v_pk_mul_f32 v[12:13], v[160:161], v[12:13]
	v_pk_mul_f32 v[166:167], v[154:155], v[166:167]
	v_pk_mul_f32 v[164:165], v[152:153], v[164:165]
	v_pk_mul_f32 v[170:171], v[158:159], v[170:171]
	v_pk_mul_f32 v[168:169], v[156:157], v[168:169]
	ds_write_b128 v80, v[8:11]
	ds_write_b128 v80, v[12:15] offset:64
	ds_write_b128 v80, v[164:167] offset:128
	ds_write_b128 v80, v[168:171] offset:192
	v_lshlrev_b64 v[8:9], 9, v[86:87]
	v_and_b32_e32 v10, 7, v194
	s_lshl_b64 s[36:37], s[60:61], 1
	v_lshl_add_u64 v[8:9], v[8:9], 0, s[8:9]
	v_lshlrev_b32_e32 v80, 4, v10
	s_add_u32 s36, s18, s36
	v_lshl_add_u64 v[8:9], v[8:9], 0, v[80:81]
	s_addc_u32 s37, s19, s37
	s_nop 1
	v_lshl_add_u64 v[8:9], s[36:37], 0, v[8:9]
	s_mov_b64 s[36:37], 0x51ff500
	v_lshl_add_u64 v[164:165], v[8:9], 0, s[36:37]
	v_mul_lo_u32 v8, v86, s77
	v_lshlrev_b32_e32 v9, 5, v10
	v_add3_u32 v80, v8, v9, s50
	s_mov_b32 s0, 0

.LBB0_684:
	v_mad_u32_u24 v80, v202, s77, v196
	ds_write_b128 v80, v[8:11]
	ds_write_b128 v80, v[164:167] offset:64
	ds_write_b128 v80, v[12:15] offset:128
	ds_write_b128 v80, v[168:171] offset:192
	v_mov_b64_e32 v[8:9], s[28:29]
	s_movk_i32 s0, 0x300
	v_mad_i64_i32 v[8:9], s[2:3], v86, s0, v[8:9]
	s_lshl_b32 s0, s16, 8
	v_readlane_b32 s2, v254, 33
	s_or_b32 s60, s2, s0
	v_and_b32_e32 v10, 7, v194
	s_lshl_b64 s[2:3], s[60:61], 1
	v_lshlrev_b32_e32 v80, 4, v10
	s_add_u32 s2, s18, s2
	v_lshl_add_u64 v[8:9], v[8:9], 0, v[80:81]
	s_addc_u32 s3, s19, s3
	s_nop 1
	v_lshl_add_u64 v[8:9], s[2:3], 0, v[8:9]
	s_mov_b64 s[2:3], 0x47ffa00
	v_lshl_add_u64 v[164:165], v[8:9], 0, s[2:3]
	v_mul_lo_u32 v8, v86, s77
	v_lshlrev_b32_e32 v9, 5, v10
	v_add3_u32 v80, v8, v9, s50
	s_mov_b32 s0, 0
	s_mov_b32 s2, 0x3e38aa3b

.LBB0_687:
	s_andn2_b64 vcc, exec, s[44:45]
	s_cbranch_vccnz .LBB0_690
	s_lshl_b32 s0, s16, 8
	v_readlane_b32 s2, v254, 33
	v_mad_u32_u24 v8, v202, s77, v196
	v_ashrrev_i32_e32 v87, 31, v86
	s_or_b32 s60, s2, s0
	ds_write_b128 v8, v[82:85]
	ds_write_b128 v8, v[160:163] offset:64
	ds_write_b128 v8, v[152:155] offset:128
	ds_write_b128 v8, v[156:159] offset:192
	v_lshlrev_b64 v[8:9], 9, v[86:87]
	v_and_b32_e32 v10, 7, v194
	s_lshl_b64 s[2:3], s[60:61], 1
	v_lshl_add_u64 v[8:9], v[8:9], 0, s[8:9]
	v_lshlrev_b32_e32 v80, 4, v10
	s_add_u32 s2, s18, s2
	v_lshl_add_u64 v[8:9], v[8:9], 0, v[80:81]
	s_addc_u32 s3, s19, s3
	s_nop 1
	v_lshl_add_u64 v[8:9], s[2:3], 0, v[8:9]
	s_mov_b64 s[2:3], 0x43ffc00
	v_lshl_add_u64 v[164:165], v[8:9], 0, s[2:3]
	v_mul_lo_u32 v8, v86, s77
	v_lshlrev_b32_e32 v9, 5, v10
	v_add3_u32 v80, v8, v9, s50
	s_mov_b32 s0, 0

.LBB0_695:
	s_lshl_b32 s0, s16, 8
	v_readlane_b32 s2, v254, 33
	v_mad_u32_u24 v80, v202, s77, v196
	v_ashrrev_i32_e32 v87, 31, v86
	s_or_b32 s60, s2, s0
	ds_write_b128 v80, v[8:11]
	ds_write_b128 v80, v[12:15] offset:64
	ds_write_b128 v80, v[164:167] offset:128
	ds_write_b128 v80, v[168:171] offset:192
	v_lshlrev_b64 v[8:9], 9, v[86:87]
	v_and_b32_e32 v10, 7, v194
	s_lshl_b64 s[2:3], s[60:61], 1
	v_lshl_add_u64 v[8:9], v[8:9], 0, s[8:9]
	v_lshlrev_b32_e32 v80, 4, v10
	s_add_u32 s2, s18, s2
	v_lshl_add_u64 v[8:9], v[8:9], 0, v[80:81]
	s_addc_u32 s3, s19, s3
	s_nop 1
	v_lshl_add_u64 v[8:9], s[2:3], 0, v[8:9]
	s_mov_b64 s[2:3], 0x3fffe00
	v_lshl_add_u64 v[164:165], v[8:9], 0, s[2:3]
	v_mul_lo_u32 v8, v86, s77
	v_lshlrev_b32_e32 v9, 5, v10
	v_add3_u32 v80, v8, v9, s50
	s_mov_b32 s0, 0
	s_mov_b32 s2, 0x3e000000

.LBB0_701:
	s_lshl_b32 s0, s16, 8
	v_readlane_b32 s2, v254, 33
	s_or_b32 s2, s2, s0
	v_mad_u32_u24 v8, v202, s77, v196
	v_ashrrev_i32_e32 v87, 31, v86
	s_ashr_i32 s3, s2, 31
	ds_write_b128 v8, v[82:85]
	ds_write_b128 v8, v[160:163] offset:64
	ds_write_b128 v8, v[152:155] offset:128
	ds_write_b128 v8, v[156:159] offset:192
	v_lshlrev_b64 v[8:9], 9, v[86:87]
	v_and_b32_e32 v10, 7, v194
	s_lshl_b64 s[2:3], s[2:3], 1
	v_lshl_add_u64 v[8:9], v[8:9], 0, s[8:9]
	v_lshlrev_b32_e32 v80, 4, v10
	s_add_u32 s2, s18, s2
	s_nop 1
	v_lshl_add_u64 v[8:9], v[8:9], 0, v[80:81]
	s_addc_u32 s3, s19, s3
	v_lshl_add_u64 v[8:9], s[2:3], 0, v[8:9]
	s_mov_b64 s[2:3], 0x3c00000
	v_mul_lo_u32 v11, v86, s77
	v_lshlrev_b32_e32 v10, 5, v10
	v_lshl_add_u64 v[8:9], v[8:9], 0, s[2:3]
	v_add3_u32 v10, v11, v10, s50
	s_mov_b32 s0, 0

.LBB0_771:
	v_mad_u32_u24 v80, v202, s77, v196
	ds_write_b128 v80, v[8:11]
	ds_write_b128 v80, v[12:15] offset:64
	ds_write_b128 v80, v[152:155] offset:128
	ds_write_b128 v80, v[156:159] offset:192
	v_readlane_b32 s36, v254, 37
	s_nop 1
	v_readlane_b32 s37, v254, 38
	s_andn2_b64 vcc, exec, s[36:37]
	s_cbranch_vccnz .LBB0_774
	s_lshl_b64 s[36:37], s[34:35], 15
	s_lshl_b32 s0, s2, 7
	v_ashrrev_i32_e32 v87, 31, v86
	s_add_u32 s36, s0, s36
	v_lshlrev_b64 v[8:9], 7, v[86:87]
	s_addc_u32 s37, 0, s37
	v_lshlrev_b32_e32 v10, 4, v194
	v_lshl_add_u64 v[8:9], s[36:37], 0, v[8:9]
	v_and_b32_e32 v10, 0x70, v10
	v_or_b32_e32 v8, v8, v10
	v_lshl_add_u64 v[8:9], s[42:43], 0, v[8:9]
	s_mov_b64 s[36:37], 0x4000000
	v_mul_lo_u32 v11, v86, s77
	v_lshl_add_u64 v[8:9], v[8:9], 0, s[36:37]
	v_add3_u32 v10, v11, v10, s97
	s_mov_b32 s0, 0

.LBB0_777:
	v_mov_b64_e32 v[14:15], v[6:7]
	s_andn2_b64 vcc, exec, s[44:45]
	v_mov_b64_e32 v[12:13], v[4:5]
	v_mov_b64_e32 v[10:11], v[2:3]
	v_mov_b64_e32 v[8:9], v[0:1]
	s_cbranch_vccnz .LBB0_786
	s_cmp_lg_u32 s58, 13
	s_mov_b64 s[44:45], -1
	s_cbranch_scc0 .LBB0_782
	v_mul_f32_e32 v80, 0xbfb8aa3b, v152
	v_exp_f32_e32 v80, v80
	v_mul_f32_e32 v87, 0xbfb8aa3b, v153
	v_exp_f32_e32 v87, v87
	v_mul_f32_e32 v165, 0xbfb8aa3b, v155
	v_add_f32_e32 v80, 1.0, v80
	v_rcp_f32_e32 v164, v80
	v_add_f32_e32 v80, 1.0, v87
	v_mul_f32_e32 v87, 0xbfb8aa3b, v154
	v_exp_f32_e32 v87, v87
	v_exp_f32_e32 v167, v165
	v_rcp_f32_e32 v165, v80
	v_mul_f32_e32 v8, 0xbfb8aa3b, v82
	v_add_f32_e32 v80, 1.0, v87
	v_mul_f32_e32 v87, 0xbfb8aa3b, v156
	v_rcp_f32_e32 v166, v80
	v_add_f32_e32 v80, 1.0, v167
	v_exp_f32_e32 v87, v87
	v_mul_f32_e32 v167, 0xbfb8aa3b, v157
	v_exp_f32_e32 v169, v167
	v_mul_f32_e32 v9, 0xbfb8aa3b, v83
	v_mul_f32_e32 v10, 0xbfb8aa3b, v84
	v_mul_f32_e32 v11, 0xbfb8aa3b, v85
	v_rcp_f32_e32 v167, v80
	v_add_f32_e32 v80, 1.0, v87
	v_mul_f32_e32 v87, 0xbfb8aa3b, v158
	v_exp_f32_e32 v8, v8
	v_exp_f32_e32 v9, v9
	v_exp_f32_e32 v10, v10
	v_exp_f32_e32 v11, v11
	v_mul_f32_e32 v12, 0xbfb8aa3b, v160
	v_mul_f32_e32 v13, 0xbfb8aa3b, v161
	v_mul_f32_e32 v14, 0xbfb8aa3b, v162
	v_mul_f32_e32 v15, 0xbfb8aa3b, v163
	v_rcp_f32_e32 v168, v80
	v_add_f32_e32 v80, 1.0, v169
	v_exp_f32_e32 v87, v87
	v_mul_f32_e32 v169, 0xbfb8aa3b, v159
	v_exp_f32_e32 v12, v12
	v_exp_f32_e32 v13, v13
	v_exp_f32_e32 v14, v14
	v_exp_f32_e32 v15, v15
	v_exp_f32_e32 v171, v169
	v_add_f32_e32 v8, 1.0, v8
	v_add_f32_e32 v9, 1.0, v9
	v_add_f32_e32 v10, 1.0, v10
	v_add_f32_e32 v11, 1.0, v11
	v_rcp_f32_e32 v169, v80
	v_add_f32_e32 v80, 1.0, v87
	v_rcp_f32_e32 v8, v8
	v_rcp_f32_e32 v9, v9
	v_rcp_f32_e32 v10, v10
	v_rcp_f32_e32 v11, v11
	v_add_f32_e32 v12, 1.0, v12
	v_add_f32_e32 v13, 1.0, v13
	v_add_f32_e32 v14, 1.0, v14
	v_add_f32_e32 v15, 1.0, v15
	v_rcp_f32_e32 v170, v80
	v_add_f32_e32 v80, 1.0, v171
	v_rcp_f32_e32 v12, v12
	v_rcp_f32_e32 v13, v13
	v_rcp_f32_e32 v14, v14
	v_rcp_f32_e32 v15, v15
	v_rcp_f32_e32 v171, v80
	v_pk_mul_f32 v[8:9], v[82:83], v[8:9]
	v_pk_mul_f32 v[10:11], v[84:85], v[10:11]
	v_mad_u32_u24 v80, v202, s77, v196
	v_ashrrev_i32_e32 v87, 31, v86
	v_readlane_b32 s36, v254, 54
	s_lshl_b32 s0, s16, 8
	v_readlane_b32 s3, v254, 33
	v_pk_mul_f32 v[12:13], v[160:161], v[12:13]
	v_pk_mul_f32 v[14:15], v[162:163], v[14:15]
	v_pk_mul_f32 v[164:165], v[152:153], v[164:165]
	v_pk_mul_f32 v[166:167], v[154:155], v[166:167]
	v_pk_mul_f32 v[168:169], v[156:157], v[168:169]
	v_pk_mul_f32 v[170:171], v[158:159], v[170:171]
	ds_write_b128 v80, v[8:11]
	ds_write_b128 v80, v[12:15] offset:64
	ds_write_b128 v80, v[164:167] offset:128
	ds_write_b128 v80, v[168:171] offset:192
	v_lshlrev_b64 v[8:9], 11, v[86:87]
	v_readlane_b32 s37, v254, 55
	s_or_b32 s60, s3, s0
	v_and_b32_e32 v10, 7, v194
	v_lshl_add_u64 v[8:9], v[8:9], 0, s[36:37]
	s_lshl_b64 s[36:37], s[60:61], 1
	v_lshlrev_b32_e32 v80, 4, v10
	s_add_u32 s36, s18, s36
	s_nop 1
	v_lshl_add_u64 v[8:9], v[8:9], 0, v[80:81]
	s_addc_u32 s37, s19, s37
	v_lshl_add_u64 v[8:9], s[36:37], 0, v[8:9]
	s_mov_b64 s[36:37], 0x590f200
	v_mul_lo_u32 v11, v86, s77
	v_lshlrev_b32_e32 v10, 5, v10
	v_lshl_add_u64 v[8:9], v[8:9], 0, s[36:37]
	v_add3_u32 v10, v11, v10, s50
	s_mov_b32 s0, 0
	s_mov_b64 s[36:37], 0x4000

.LBB0_790:
	s_or_b64 exec, exec, s[44:45]
	s_waitcnt lgkmcnt(0)
	ds_read_b128 v[8:11], v201 offset:256
	ds_read_b128 v[12:15], v201 offset:320
	ds_read_b128 v[164:167], v201 offset:384
	ds_read_b128 v[168:171], v201 offset:448
	s_lshl_b32 s0, s16, 8
	v_readlane_b32 s3, v254, 33
	s_waitcnt lgkmcnt(0)
	v_pk_mul_f32 v[10:11], v[84:85], v[10:11]
	v_pk_mul_f32 v[8:9], v[82:83], v[8:9]
	v_mad_u32_u24 v80, v202, s77, v196
	v_ashrrev_i32_e32 v87, 31, v86
	s_or_b32 s60, s3, s0
	v_pk_mul_f32 v[14:15], v[162:163], v[14:15]
	v_pk_mul_f32 v[12:13], v[160:161], v[12:13]
	v_pk_mul_f32 v[166:167], v[154:155], v[166:167]
	v_pk_mul_f32 v[164:165], v[152:153], v[164:165]
	v_pk_mul_f32 v[170:171], v[158:159], v[170:171]
	v_pk_mul_f32 v[168:169], v[156:157], v[168:169]
	ds_write_b128 v80, v[8:11]
	ds_write_b128 v80, v[12:15] offset:64
	ds_write_b128 v80, v[164:167] offset:128
	ds_write_b128 v80, v[168:171] offset:192
	v_lshlrev_b64 v[8:9], 9, v[86:87]
	v_and_b32_e32 v10, 7, v194
	s_lshl_b64 s[36:37], s[60:61], 1
	v_lshl_add_u64 v[8:9], v[8:9], 0, s[8:9]
	v_lshlrev_b32_e32 v80, 4, v10
	s_add_u32 s36, s18, s36
	v_lshl_add_u64 v[8:9], v[8:9], 0, v[80:81]
	s_addc_u32 s37, s19, s37
	s_nop 1
	v_lshl_add_u64 v[8:9], s[36:37], 0, v[8:9]
	s_mov_b64 s[36:37], 0x5203500
	v_lshl_add_u64 v[164:165], v[8:9], 0, s[36:37]
	v_mul_lo_u32 v8, v86, s77
	v_lshlrev_b32_e32 v9, 5, v10
	v_add3_u32 v80, v8, v9, s50
	s_mov_b32 s0, 0

.LBB0_820:
	v_mad_u32_u24 v80, v202, s77, v196
	ds_write_b128 v80, v[8:11]
	ds_write_b128 v80, v[164:167] offset:64
	ds_write_b128 v80, v[12:15] offset:128
	ds_write_b128 v80, v[168:171] offset:192
	v_mov_b64_e32 v[8:9], s[28:29]
	s_movk_i32 s0, 0x300
	v_mad_i64_i32 v[8:9], s[2:3], v86, s0, v[8:9]
	s_lshl_b32 s0, s16, 8
	v_readlane_b32 s2, v254, 33
	s_or_b32 s60, s2, s0
	v_and_b32_e32 v10, 7, v194
	s_lshl_b64 s[2:3], s[60:61], 1
	v_lshlrev_b32_e32 v80, 4, v10
	s_add_u32 s2, s18, s2
	v_lshl_add_u64 v[8:9], v[8:9], 0, v[80:81]
	s_addc_u32 s3, s19, s3
	s_nop 1
	v_lshl_add_u64 v[8:9], s[2:3], 0, v[8:9]
	s_mov_b64 s[2:3], 0x4805a00
	v_lshl_add_u64 v[164:165], v[8:9], 0, s[2:3]
	v_mul_lo_u32 v8, v86, s77
	v_lshlrev_b32_e32 v9, 5, v10
	v_add3_u32 v80, v8, v9, s50
	s_mov_b32 s0, 0
	s_mov_b32 s2, 0x3e38aa3b

.LBB0_823:
	s_andn2_b64 vcc, exec, s[44:45]
	s_cbranch_vccnz .LBB0_826
	s_lshl_b32 s0, s16, 8
	v_readlane_b32 s2, v254, 33
	v_mad_u32_u24 v8, v202, s77, v196
	v_ashrrev_i32_e32 v87, 31, v86
	s_or_b32 s60, s2, s0
	ds_write_b128 v8, v[82:85]
	ds_write_b128 v8, v[160:163] offset:64
	ds_write_b128 v8, v[152:155] offset:128
	ds_write_b128 v8, v[156:159] offset:192
	v_lshlrev_b64 v[8:9], 9, v[86:87]
	v_and_b32_e32 v10, 7, v194
	s_lshl_b64 s[2:3], s[60:61], 1
	v_lshl_add_u64 v[8:9], v[8:9], 0, s[8:9]
	v_lshlrev_b32_e32 v80, 4, v10
	s_add_u32 s2, s18, s2
	v_lshl_add_u64 v[8:9], v[8:9], 0, v[80:81]
	s_addc_u32 s3, s19, s3
	s_nop 1
	v_lshl_add_u64 v[8:9], s[2:3], 0, v[8:9]
	s_mov_b64 s[2:3], 0x4403c00
	v_lshl_add_u64 v[164:165], v[8:9], 0, s[2:3]
	v_mul_lo_u32 v8, v86, s77
	v_lshlrev_b32_e32 v9, 5, v10
	v_add3_u32 v80, v8, v9, s50
	s_mov_b32 s0, 0

.LBB0_831:
	s_lshl_b32 s0, s16, 8
	v_readlane_b32 s2, v254, 33
	v_mad_u32_u24 v80, v202, s77, v196
	v_ashrrev_i32_e32 v87, 31, v86
	s_or_b32 s60, s2, s0
	ds_write_b128 v80, v[8:11]
	ds_write_b128 v80, v[12:15] offset:64
	ds_write_b128 v80, v[164:167] offset:128
	ds_write_b128 v80, v[168:171] offset:192
	v_lshlrev_b64 v[8:9], 9, v[86:87]
	v_and_b32_e32 v10, 7, v194
	s_lshl_b64 s[2:3], s[60:61], 1
	v_lshl_add_u64 v[8:9], v[8:9], 0, s[8:9]
	v_lshlrev_b32_e32 v80, 4, v10
	s_add_u32 s2, s18, s2
	v_lshl_add_u64 v[8:9], v[8:9], 0, v[80:81]
	s_addc_u32 s3, s19, s3
	s_nop 1
	v_lshl_add_u64 v[8:9], s[2:3], 0, v[8:9]
	s_mov_b64 s[2:3], 0x4003e00
	v_lshl_add_u64 v[164:165], v[8:9], 0, s[2:3]
	v_mul_lo_u32 v8, v86, s77
	v_lshlrev_b32_e32 v9, 5, v10
	v_add3_u32 v80, v8, v9, s50
	s_mov_b32 s0, 0
	s_mov_b32 s2, 0x3e000000

.LBB0_837:
	s_lshl_b32 s0, s16, 8
	v_readlane_b32 s2, v254, 33
	s_or_b32 s2, s2, s0
	v_mad_u32_u24 v8, v202, s77, v196
	v_ashrrev_i32_e32 v87, 31, v86
	s_ashr_i32 s3, s2, 31
	ds_write_b128 v8, v[82:85]
	ds_write_b128 v8, v[160:163] offset:64
	ds_write_b128 v8, v[152:155] offset:128
	ds_write_b128 v8, v[156:159] offset:192
	v_lshlrev_b64 v[8:9], 9, v[86:87]
	v_and_b32_e32 v10, 7, v194
	s_lshl_b64 s[2:3], s[2:3], 1
	v_lshl_add_u64 v[8:9], v[8:9], 0, s[8:9]
	v_lshlrev_b32_e32 v80, 4, v10
	s_add_u32 s2, s18, s2
	s_nop 1
	v_lshl_add_u64 v[8:9], v[8:9], 0, v[80:81]
	s_addc_u32 s3, s19, s3
	v_lshl_add_u64 v[8:9], s[2:3], 0, v[8:9]
	s_mov_b64 s[2:3], 0x3c04000
	v_mul_lo_u32 v11, v86, s77
	v_lshlrev_b32_e32 v10, 5, v10
	v_lshl_add_u64 v[8:9], v[8:9], 0, s[2:3]
	v_add3_u32 v10, v11, v10, s50
	s_mov_b32 s0, 0

.LBB0_913:
	v_mov_b64_e32 v[14:15], v[6:7]
	s_andn2_b64 vcc, exec, s[44:45]
	v_mov_b64_e32 v[12:13], v[4:5]
	v_mov_b64_e32 v[10:11], v[2:3]
	v_mov_b64_e32 v[8:9], v[0:1]
	s_cbranch_vccnz .LBB0_922
	s_cmp_lg_u32 s58, 13
	s_mov_b64 s[44:45], -1
	s_cbranch_scc0 .LBB0_918
	v_mul_f32_e32 v80, 0xbfb8aa3b, v152
	v_exp_f32_e32 v80, v80
	v_mul_f32_e32 v87, 0xbfb8aa3b, v153
	v_exp_f32_e32 v87, v87
	v_mul_f32_e32 v165, 0xbfb8aa3b, v155
	v_add_f32_e32 v80, 1.0, v80
	v_rcp_f32_e32 v164, v80
	v_add_f32_e32 v80, 1.0, v87
	v_mul_f32_e32 v87, 0xbfb8aa3b, v154
	v_exp_f32_e32 v87, v87
	v_exp_f32_e32 v167, v165
	v_rcp_f32_e32 v165, v80
	v_mul_f32_e32 v8, 0xbfb8aa3b, v82
	v_add_f32_e32 v80, 1.0, v87
	v_mul_f32_e32 v87, 0xbfb8aa3b, v156
	v_rcp_f32_e32 v166, v80
	v_add_f32_e32 v80, 1.0, v167
	v_exp_f32_e32 v87, v87
	v_mul_f32_e32 v167, 0xbfb8aa3b, v157
	v_exp_f32_e32 v169, v167
	v_mul_f32_e32 v9, 0xbfb8aa3b, v83
	v_mul_f32_e32 v10, 0xbfb8aa3b, v84
	v_mul_f32_e32 v11, 0xbfb8aa3b, v85
	v_rcp_f32_e32 v167, v80
	v_add_f32_e32 v80, 1.0, v87
	v_mul_f32_e32 v87, 0xbfb8aa3b, v158
	v_exp_f32_e32 v8, v8
	v_exp_f32_e32 v9, v9
	v_exp_f32_e32 v10, v10
	v_exp_f32_e32 v11, v11
	v_mul_f32_e32 v12, 0xbfb8aa3b, v160
	v_mul_f32_e32 v13, 0xbfb8aa3b, v161
	v_mul_f32_e32 v14, 0xbfb8aa3b, v162
	v_mul_f32_e32 v15, 0xbfb8aa3b, v163
	v_rcp_f32_e32 v168, v80
	v_add_f32_e32 v80, 1.0, v169
	v_exp_f32_e32 v87, v87
	v_mul_f32_e32 v169, 0xbfb8aa3b, v159
	v_exp_f32_e32 v12, v12
	v_exp_f32_e32 v13, v13
	v_exp_f32_e32 v14, v14
	v_exp_f32_e32 v15, v15
	v_exp_f32_e32 v171, v169
	v_add_f32_e32 v8, 1.0, v8
	v_add_f32_e32 v9, 1.0, v9
	v_add_f32_e32 v10, 1.0, v10
	v_add_f32_e32 v11, 1.0, v11
	v_rcp_f32_e32 v169, v80
	v_add_f32_e32 v80, 1.0, v87
	v_rcp_f32_e32 v8, v8
	v_rcp_f32_e32 v9, v9
	v_rcp_f32_e32 v10, v10
	v_rcp_f32_e32 v11, v11
	v_add_f32_e32 v12, 1.0, v12
	v_add_f32_e32 v13, 1.0, v13
	v_add_f32_e32 v14, 1.0, v14
	v_add_f32_e32 v15, 1.0, v15
	v_rcp_f32_e32 v170, v80
	v_add_f32_e32 v80, 1.0, v171
	v_rcp_f32_e32 v12, v12
	v_rcp_f32_e32 v13, v13
	v_rcp_f32_e32 v14, v14
	v_rcp_f32_e32 v15, v15
	v_rcp_f32_e32 v171, v80
	v_pk_mul_f32 v[8:9], v[82:83], v[8:9]
	v_pk_mul_f32 v[10:11], v[84:85], v[10:11]
	v_mad_u32_u24 v80, v202, s77, v196
	v_ashrrev_i32_e32 v87, 31, v86
	v_readlane_b32 s36, v254, 54
	s_lshl_b32 s0, s16, 8
	v_readlane_b32 s3, v254, 33
	v_pk_mul_f32 v[12:13], v[160:161], v[12:13]
	v_pk_mul_f32 v[14:15], v[162:163], v[14:15]
	v_pk_mul_f32 v[164:165], v[152:153], v[164:165]
	v_pk_mul_f32 v[166:167], v[154:155], v[166:167]
	v_pk_mul_f32 v[168:169], v[156:157], v[168:169]
	v_pk_mul_f32 v[170:171], v[158:159], v[170:171]
	ds_write_b128 v80, v[8:11]
	ds_write_b128 v80, v[12:15] offset:64
	ds_write_b128 v80, v[164:167] offset:128
	ds_write_b128 v80, v[168:171] offset:192
	v_lshlrev_b64 v[8:9], 11, v[86:87]
	v_readlane_b32 s37, v254, 55
	s_or_b32 s60, s3, s0
	v_and_b32_e32 v10, 7, v194
	v_lshl_add_u64 v[8:9], v[8:9], 0, s[36:37]
	s_lshl_b64 s[36:37], s[60:61], 1
	v_lshlrev_b32_e32 v80, 4, v10
	s_add_u32 s36, s18, s36
	s_nop 1
	v_lshl_add_u64 v[8:9], v[8:9], 0, v[80:81]
	s_addc_u32 s37, s19, s37
	v_lshl_add_u64 v[8:9], s[36:37], 0, v[8:9]
	s_mov_b64 s[36:37], 0x591f200
	v_mul_lo_u32 v11, v86, s77
	v_lshlrev_b32_e32 v10, 5, v10
	v_lshl_add_u64 v[8:9], v[8:9], 0, s[36:37]
	v_add3_u32 v10, v11, v10, s50
	s_mov_b32 s0, 0
	s_mov_b64 s[36:37], 0x4000

.LBB0_926:
	s_or_b64 exec, exec, s[44:45]
	s_waitcnt lgkmcnt(0)
	ds_read_b128 v[8:11], v201 offset:256
	ds_read_b128 v[12:15], v201 offset:320
	ds_read_b128 v[164:167], v201 offset:384
	ds_read_b128 v[168:171], v201 offset:448
	s_lshl_b32 s0, s16, 8
	v_readlane_b32 s3, v254, 33
	s_waitcnt lgkmcnt(0)
	v_pk_mul_f32 v[10:11], v[84:85], v[10:11]
	v_pk_mul_f32 v[8:9], v[82:83], v[8:9]
	v_mad_u32_u24 v80, v202, s77, v196
	v_ashrrev_i32_e32 v87, 31, v86
	s_or_b32 s60, s3, s0
	v_pk_mul_f32 v[14:15], v[162:163], v[14:15]
	v_pk_mul_f32 v[12:13], v[160:161], v[12:13]
	v_pk_mul_f32 v[166:167], v[154:155], v[166:167]
	v_pk_mul_f32 v[164:165], v[152:153], v[164:165]
	v_pk_mul_f32 v[170:171], v[158:159], v[170:171]
	v_pk_mul_f32 v[168:169], v[156:157], v[168:169]
	ds_write_b128 v80, v[8:11]
	ds_write_b128 v80, v[12:15] offset:64
	ds_write_b128 v80, v[164:167] offset:128
	ds_write_b128 v80, v[168:171] offset:192
	v_lshlrev_b64 v[8:9], 9, v[86:87]
	v_and_b32_e32 v10, 7, v194
	s_lshl_b64 s[36:37], s[60:61], 1
	v_lshl_add_u64 v[8:9], v[8:9], 0, s[8:9]
	v_lshlrev_b32_e32 v80, 4, v10
	s_add_u32 s36, s18, s36
	v_lshl_add_u64 v[8:9], v[8:9], 0, v[80:81]
	s_addc_u32 s37, s19, s37
	s_nop 1
	v_lshl_add_u64 v[8:9], s[36:37], 0, v[8:9]
	s_mov_b64 s[36:37], 0x5207500
	v_lshl_add_u64 v[164:165], v[8:9], 0, s[36:37]
	v_mul_lo_u32 v8, v86, s77
	v_lshlrev_b32_e32 v9, 5, v10
	v_add3_u32 v80, v8, v9, s50
	s_mov_b32 s0, 0

.LBB0_956:
	v_mad_u32_u24 v80, v202, s77, v196
	ds_write_b128 v80, v[8:11]
	ds_write_b128 v80, v[164:167] offset:64
	ds_write_b128 v80, v[12:15] offset:128
	ds_write_b128 v80, v[168:171] offset:192
	v_mov_b64_e32 v[8:9], s[28:29]
	s_movk_i32 s0, 0x300
	v_mad_i64_i32 v[8:9], s[2:3], v86, s0, v[8:9]
	s_lshl_b32 s0, s16, 8
	v_readlane_b32 s2, v254, 33
	s_or_b32 s60, s2, s0
	v_and_b32_e32 v10, 7, v194
	s_lshl_b64 s[2:3], s[60:61], 1
	v_lshlrev_b32_e32 v80, 4, v10
	s_add_u32 s2, s18, s2
	v_lshl_add_u64 v[8:9], v[8:9], 0, v[80:81]
	s_addc_u32 s3, s19, s3
	s_nop 1
	v_lshl_add_u64 v[8:9], s[2:3], 0, v[8:9]
	s_mov_b64 s[2:3], 0x480ba00
	v_lshl_add_u64 v[164:165], v[8:9], 0, s[2:3]
	v_mul_lo_u32 v8, v86, s77
	v_lshlrev_b32_e32 v9, 5, v10
	v_add3_u32 v80, v8, v9, s50
	s_mov_b32 s0, 0
	s_mov_b32 s2, 0x3e38aa3b

.LBB0_959:
	s_andn2_b64 vcc, exec, s[44:45]
	s_cbranch_vccnz .LBB0_962
	s_lshl_b32 s0, s16, 8
	v_readlane_b32 s2, v254, 33
	v_mad_u32_u24 v8, v202, s77, v196
	v_ashrrev_i32_e32 v87, 31, v86
	s_or_b32 s60, s2, s0
	ds_write_b128 v8, v[82:85]
	ds_write_b128 v8, v[160:163] offset:64
	ds_write_b128 v8, v[152:155] offset:128
	ds_write_b128 v8, v[156:159] offset:192
	v_lshlrev_b64 v[8:9], 9, v[86:87]
	v_and_b32_e32 v10, 7, v194
	s_lshl_b64 s[2:3], s[60:61], 1
	v_lshl_add_u64 v[8:9], v[8:9], 0, s[8:9]
	v_lshlrev_b32_e32 v80, 4, v10
	s_add_u32 s2, s18, s2
	v_lshl_add_u64 v[8:9], v[8:9], 0, v[80:81]
	s_addc_u32 s3, s19, s3
	s_nop 1
	v_lshl_add_u64 v[8:9], s[2:3], 0, v[8:9]
	s_mov_b64 s[2:3], 0x4407c00
	v_lshl_add_u64 v[164:165], v[8:9], 0, s[2:3]
	v_mul_lo_u32 v8, v86, s77
	v_lshlrev_b32_e32 v9, 5, v10
	v_add3_u32 v80, v8, v9, s50
	s_mov_b32 s0, 0

.LBB0_967:
	s_lshl_b32 s0, s16, 8
	v_readlane_b32 s2, v254, 33
	v_mad_u32_u24 v80, v202, s77, v196
	v_ashrrev_i32_e32 v87, 31, v86
	s_or_b32 s60, s2, s0
	ds_write_b128 v80, v[8:11]
	ds_write_b128 v80, v[12:15] offset:64
	ds_write_b128 v80, v[164:167] offset:128
	ds_write_b128 v80, v[168:171] offset:192
	v_lshlrev_b64 v[8:9], 9, v[86:87]
	v_and_b32_e32 v10, 7, v194
	s_lshl_b64 s[2:3], s[60:61], 1
	v_lshl_add_u64 v[8:9], v[8:9], 0, s[8:9]
	v_lshlrev_b32_e32 v80, 4, v10
	s_add_u32 s2, s18, s2
	v_lshl_add_u64 v[8:9], v[8:9], 0, v[80:81]
	s_addc_u32 s3, s19, s3
	s_nop 1
	v_lshl_add_u64 v[8:9], s[2:3], 0, v[8:9]
	s_mov_b64 s[2:3], 0x4007e00
	v_lshl_add_u64 v[164:165], v[8:9], 0, s[2:3]
	v_mul_lo_u32 v8, v86, s77
	v_lshlrev_b32_e32 v9, 5, v10
	v_add3_u32 v80, v8, v9, s50
	s_mov_b32 s0, 0
	s_mov_b32 s2, 0x3e000000

.LBB0_973:
	s_lshl_b32 s0, s16, 8
	v_readlane_b32 s2, v254, 33
	s_or_b32 s2, s2, s0
	v_mad_u32_u24 v8, v202, s77, v196
	v_ashrrev_i32_e32 v87, 31, v86
	s_ashr_i32 s3, s2, 31
	ds_write_b128 v8, v[82:85]
	ds_write_b128 v8, v[160:163] offset:64
	ds_write_b128 v8, v[152:155] offset:128
	ds_write_b128 v8, v[156:159] offset:192
	v_lshlrev_b64 v[8:9], 9, v[86:87]
	v_and_b32_e32 v10, 7, v194
	s_lshl_b64 s[2:3], s[2:3], 1
	v_lshl_add_u64 v[8:9], v[8:9], 0, s[8:9]
	v_lshlrev_b32_e32 v80, 4, v10
	s_add_u32 s2, s18, s2
	s_nop 1
	v_lshl_add_u64 v[8:9], v[8:9], 0, v[80:81]
	s_addc_u32 s3, s19, s3
	v_lshl_add_u64 v[8:9], s[2:3], 0, v[8:9]
	s_mov_b64 s[2:3], 0x3c08000
	v_mul_lo_u32 v11, v86, s77
	v_lshlrev_b32_e32 v10, 5, v10
	v_lshl_add_u64 v[8:9], v[8:9], 0, s[2:3]
	v_add3_u32 v10, v11, v10, s50
	s_mov_b32 s0, 0

.LBB0_1043:
	v_mad_u32_u24 v80, v202, s77, v196
	ds_write_b128 v80, v[8:11]
	ds_write_b128 v80, v[12:15] offset:64
	ds_write_b128 v80, v[152:155] offset:128
	ds_write_b128 v80, v[156:159] offset:192
	v_readlane_b32 s26, v254, 37
	s_nop 1
	v_readlane_b32 s27, v254, 38
	s_mov_b32 s3, s57
	s_andn2_b64 vcc, exec, s[26:27]
	s_cbranch_vccnz .LBB0_1046
	s_lshl_b64 s[26:27], s[34:35], 15
	s_lshl_b32 s0, s2, 7
	v_ashrrev_i32_e32 v87, 31, v86
	s_add_u32 s26, s0, s26
	v_lshlrev_b64 v[8:9], 7, v[86:87]
	s_addc_u32 s27, 0, s27
	v_lshlrev_b32_e32 v10, 4, v194
	v_lshl_add_u64 v[8:9], s[26:27], 0, v[8:9]
	v_and_b32_e32 v10, 0x70, v10
	v_or_b32_e32 v8, v8, v10
	v_lshl_add_u64 v[8:9], s[42:43], 0, v[8:9]
	s_mov_b64 s[26:27], 0x4000000
	v_mul_lo_u32 v11, v86, s77
	v_lshl_add_u64 v[8:9], v[8:9], 0, s[26:27]
	v_add3_u32 v10, v11, v10, s97
	s_mov_b32 s0, 0

.LBB0_1049:
	v_mov_b64_e32 v[14:15], v[6:7]
	s_andn2_b64 vcc, exec, s[44:45]
	v_mov_b64_e32 v[12:13], v[4:5]
	v_mov_b64_e32 v[10:11], v[2:3]
	v_mov_b64_e32 v[8:9], v[0:1]
	s_cbranch_vccnz .LBB0_1058
	s_cmp_lg_u32 s58, 13
	s_mov_b64 s[44:45], -1
	s_cbranch_scc0 .LBB0_1054
	v_mul_f32_e32 v80, 0xbfb8aa3b, v152
	v_exp_f32_e32 v80, v80
	v_mul_f32_e32 v87, 0xbfb8aa3b, v153
	v_exp_f32_e32 v87, v87
	v_mul_f32_e32 v165, 0xbfb8aa3b, v155
	v_add_f32_e32 v80, 1.0, v80
	v_rcp_f32_e32 v164, v80
	v_add_f32_e32 v80, 1.0, v87
	v_mul_f32_e32 v87, 0xbfb8aa3b, v154
	v_exp_f32_e32 v87, v87
	v_exp_f32_e32 v167, v165
	v_rcp_f32_e32 v165, v80
	v_mul_f32_e32 v8, 0xbfb8aa3b, v82
	v_add_f32_e32 v80, 1.0, v87
	v_mul_f32_e32 v87, 0xbfb8aa3b, v156
	v_rcp_f32_e32 v166, v80
	v_add_f32_e32 v80, 1.0, v167
	v_exp_f32_e32 v87, v87
	v_mul_f32_e32 v167, 0xbfb8aa3b, v157
	v_exp_f32_e32 v169, v167
	v_mul_f32_e32 v9, 0xbfb8aa3b, v83
	v_mul_f32_e32 v10, 0xbfb8aa3b, v84
	v_mul_f32_e32 v11, 0xbfb8aa3b, v85
	v_rcp_f32_e32 v167, v80
	v_add_f32_e32 v80, 1.0, v87
	v_mul_f32_e32 v87, 0xbfb8aa3b, v158
	v_exp_f32_e32 v8, v8
	v_exp_f32_e32 v9, v9
	v_exp_f32_e32 v10, v10
	v_exp_f32_e32 v11, v11
	v_mul_f32_e32 v12, 0xbfb8aa3b, v160
	v_mul_f32_e32 v13, 0xbfb8aa3b, v161
	v_mul_f32_e32 v14, 0xbfb8aa3b, v162
	v_mul_f32_e32 v15, 0xbfb8aa3b, v163
	v_rcp_f32_e32 v168, v80
	v_add_f32_e32 v80, 1.0, v169
	v_exp_f32_e32 v87, v87
	v_mul_f32_e32 v169, 0xbfb8aa3b, v159
	v_exp_f32_e32 v12, v12
	v_exp_f32_e32 v13, v13
	v_exp_f32_e32 v14, v14
	v_exp_f32_e32 v15, v15
	v_exp_f32_e32 v171, v169
	v_add_f32_e32 v8, 1.0, v8
	v_add_f32_e32 v9, 1.0, v9
	v_add_f32_e32 v10, 1.0, v10
	v_add_f32_e32 v11, 1.0, v11
	v_rcp_f32_e32 v169, v80
	v_add_f32_e32 v80, 1.0, v87
	v_rcp_f32_e32 v8, v8
	v_rcp_f32_e32 v9, v9
	v_rcp_f32_e32 v10, v10
	v_rcp_f32_e32 v11, v11
	v_add_f32_e32 v12, 1.0, v12
	v_add_f32_e32 v13, 1.0, v13
	v_add_f32_e32 v14, 1.0, v14
	v_add_f32_e32 v15, 1.0, v15
	v_rcp_f32_e32 v170, v80
	v_add_f32_e32 v80, 1.0, v171
	v_rcp_f32_e32 v12, v12
	v_rcp_f32_e32 v13, v13
	v_rcp_f32_e32 v14, v14
	v_rcp_f32_e32 v15, v15
	v_rcp_f32_e32 v171, v80
	v_pk_mul_f32 v[8:9], v[82:83], v[8:9]
	v_pk_mul_f32 v[10:11], v[84:85], v[10:11]
	v_mad_u32_u24 v80, v202, s77, v196
	v_ashrrev_i32_e32 v87, 31, v86
	v_readlane_b32 s26, v254, 54
	s_lshl_b32 s0, s16, 8
	v_readlane_b32 s3, v254, 33
	v_pk_mul_f32 v[12:13], v[160:161], v[12:13]
	v_pk_mul_f32 v[14:15], v[162:163], v[14:15]
	v_pk_mul_f32 v[164:165], v[152:153], v[164:165]
	v_pk_mul_f32 v[166:167], v[154:155], v[166:167]
	v_pk_mul_f32 v[168:169], v[156:157], v[168:169]
	v_pk_mul_f32 v[170:171], v[158:159], v[170:171]
	ds_write_b128 v80, v[8:11]
	ds_write_b128 v80, v[12:15] offset:64
	ds_write_b128 v80, v[164:167] offset:128
	ds_write_b128 v80, v[168:171] offset:192
	v_lshlrev_b64 v[8:9], 11, v[86:87]
	v_readlane_b32 s27, v254, 55
	s_or_b32 s60, s3, s0
	v_and_b32_e32 v10, 7, v194
	v_lshl_add_u64 v[8:9], v[8:9], 0, s[26:27]
	s_lshl_b64 s[26:27], s[60:61], 1
	v_lshlrev_b32_e32 v80, 4, v10
	s_add_u32 s26, s18, s26
	s_nop 1
	v_lshl_add_u64 v[8:9], v[8:9], 0, v[80:81]
	s_addc_u32 s27, s19, s27
	v_lshl_add_u64 v[8:9], s[26:27], 0, v[8:9]
	s_mov_b64 s[26:27], 0x592f200
	v_mul_lo_u32 v11, v86, s77
	v_lshlrev_b32_e32 v10, 5, v10
	v_lshl_add_u64 v[8:9], v[8:9], 0, s[26:27]
	v_add3_u32 v10, v11, v10, s50
	s_mov_b32 s0, 0
	s_mov_b64 s[26:27], 0x4000

.LBB0_1062:
	s_or_b64 exec, exec, s[44:45]
	s_waitcnt lgkmcnt(0)
	ds_read_b128 v[8:11], v201 offset:256
	ds_read_b128 v[12:15], v201 offset:320
	ds_read_b128 v[164:167], v201 offset:384
	ds_read_b128 v[168:171], v201 offset:448
	s_lshl_b32 s0, s16, 8
	v_readlane_b32 s3, v254, 33
	s_waitcnt lgkmcnt(0)
	v_pk_mul_f32 v[10:11], v[84:85], v[10:11]
	v_pk_mul_f32 v[8:9], v[82:83], v[8:9]
	v_mad_u32_u24 v80, v202, s77, v196
	v_ashrrev_i32_e32 v87, 31, v86
	s_or_b32 s60, s3, s0
	v_pk_mul_f32 v[14:15], v[162:163], v[14:15]
	v_pk_mul_f32 v[12:13], v[160:161], v[12:13]
	v_pk_mul_f32 v[166:167], v[154:155], v[166:167]
	v_pk_mul_f32 v[164:165], v[152:153], v[164:165]
	v_pk_mul_f32 v[170:171], v[158:159], v[170:171]
	v_pk_mul_f32 v[168:169], v[156:157], v[168:169]
	ds_write_b128 v80, v[8:11]
	ds_write_b128 v80, v[12:15] offset:64
	ds_write_b128 v80, v[164:167] offset:128
	ds_write_b128 v80, v[168:171] offset:192
	v_lshlrev_b64 v[8:9], 9, v[86:87]
	v_and_b32_e32 v10, 7, v194
	s_lshl_b64 s[26:27], s[60:61], 1
	v_lshl_add_u64 v[8:9], v[8:9], 0, s[8:9]
	v_lshlrev_b32_e32 v80, 4, v10
	s_add_u32 s26, s18, s26
	v_lshl_add_u64 v[8:9], v[8:9], 0, v[80:81]
	s_addc_u32 s27, s19, s27
	s_nop 1
	v_lshl_add_u64 v[8:9], s[26:27], 0, v[8:9]
	s_mov_b64 s[26:27], 0x520b500
	v_lshl_add_u64 v[164:165], v[8:9], 0, s[26:27]
	v_mul_lo_u32 v8, v86, s77
	v_lshlrev_b32_e32 v9, 5, v10
	v_add3_u32 v80, v8, v9, s50
	s_mov_b32 s0, 0

.LBB0_1092:
	v_mad_u32_u24 v80, v202, s77, v196
	ds_write_b128 v80, v[8:11]
	ds_write_b128 v80, v[164:167] offset:64
	ds_write_b128 v80, v[12:15] offset:128
	ds_write_b128 v80, v[168:171] offset:192
	v_mov_b64_e32 v[8:9], s[28:29]
	s_movk_i32 s0, 0x300
	v_mad_i64_i32 v[8:9], s[2:3], v86, s0, v[8:9]
	s_lshl_b32 s0, s16, 8
	v_readlane_b32 s2, v254, 33
	s_or_b32 s60, s2, s0
	v_and_b32_e32 v10, 7, v194
	s_lshl_b64 s[2:3], s[60:61], 1
	v_lshlrev_b32_e32 v80, 4, v10
	s_add_u32 s2, s18, s2
	v_lshl_add_u64 v[8:9], v[8:9], 0, v[80:81]
	s_addc_u32 s3, s19, s3
	s_nop 1
	v_lshl_add_u64 v[8:9], s[2:3], 0, v[8:9]
	s_mov_b64 s[2:3], 0x4811a00
	v_lshl_add_u64 v[164:165], v[8:9], 0, s[2:3]
	v_mul_lo_u32 v8, v86, s77
	v_lshlrev_b32_e32 v9, 5, v10
	v_add3_u32 v80, v8, v9, s50
	s_mov_b32 s0, 0
	s_mov_b32 s2, 0x3e38aa3b

.LBB0_1095:
	s_andn2_b64 vcc, exec, s[44:45]
	s_cbranch_vccnz .LBB0_1098
	s_lshl_b32 s0, s16, 8
	v_readlane_b32 s2, v254, 33
	v_mad_u32_u24 v8, v202, s77, v196
	v_ashrrev_i32_e32 v87, 31, v86
	s_or_b32 s60, s2, s0
	ds_write_b128 v8, v[82:85]
	ds_write_b128 v8, v[160:163] offset:64
	ds_write_b128 v8, v[152:155] offset:128
	ds_write_b128 v8, v[156:159] offset:192
	v_lshlrev_b64 v[8:9], 9, v[86:87]
	v_and_b32_e32 v10, 7, v194
	s_lshl_b64 s[2:3], s[60:61], 1
	v_lshl_add_u64 v[8:9], v[8:9], 0, s[8:9]
	v_lshlrev_b32_e32 v80, 4, v10
	s_add_u32 s2, s18, s2
	v_lshl_add_u64 v[8:9], v[8:9], 0, v[80:81]
	s_addc_u32 s3, s19, s3
	s_nop 1
	v_lshl_add_u64 v[8:9], s[2:3], 0, v[8:9]
	s_mov_b64 s[2:3], 0x440bc00
	v_lshl_add_u64 v[164:165], v[8:9], 0, s[2:3]
	v_mul_lo_u32 v8, v86, s77
	v_lshlrev_b32_e32 v9, 5, v10
	v_add3_u32 v80, v8, v9, s50
	s_mov_b32 s0, 0

.LBB0_1103:
	s_lshl_b32 s0, s16, 8
	v_readlane_b32 s2, v254, 33
	v_mad_u32_u24 v80, v202, s77, v196
	v_ashrrev_i32_e32 v87, 31, v86
	s_or_b32 s60, s2, s0
	ds_write_b128 v80, v[8:11]
	ds_write_b128 v80, v[12:15] offset:64
	ds_write_b128 v80, v[164:167] offset:128
	ds_write_b128 v80, v[168:171] offset:192
	v_lshlrev_b64 v[8:9], 9, v[86:87]
	v_and_b32_e32 v10, 7, v194
	s_lshl_b64 s[2:3], s[60:61], 1
	v_lshl_add_u64 v[8:9], v[8:9], 0, s[8:9]
	v_lshlrev_b32_e32 v80, 4, v10
	s_add_u32 s2, s18, s2
	v_lshl_add_u64 v[8:9], v[8:9], 0, v[80:81]
	s_addc_u32 s3, s19, s3
	s_nop 1
	v_lshl_add_u64 v[8:9], s[2:3], 0, v[8:9]
	s_mov_b64 s[2:3], 0x400be00
	v_lshl_add_u64 v[164:165], v[8:9], 0, s[2:3]
	v_mul_lo_u32 v8, v86, s77
	v_lshlrev_b32_e32 v9, 5, v10
	v_add3_u32 v80, v8, v9, s50
	s_mov_b32 s0, 0
	s_mov_b32 s2, 0x3e000000

.LBB0_1109:
	s_lshl_b32 s0, s16, 8
	v_readlane_b32 s2, v254, 33
	s_or_b32 s2, s2, s0
	v_mad_u32_u24 v8, v202, s77, v196
	v_ashrrev_i32_e32 v87, 31, v86
	s_ashr_i32 s3, s2, 31
	ds_write_b128 v8, v[82:85]
	ds_write_b128 v8, v[160:163] offset:64
	ds_write_b128 v8, v[152:155] offset:128
	ds_write_b128 v8, v[156:159] offset:192
	v_lshlrev_b64 v[8:9], 9, v[86:87]
	v_and_b32_e32 v10, 7, v194
	s_lshl_b64 s[2:3], s[2:3], 1
	v_lshl_add_u64 v[8:9], v[8:9], 0, s[8:9]
	v_lshlrev_b32_e32 v80, 4, v10
	s_add_u32 s2, s18, s2
	s_nop 1
	v_lshl_add_u64 v[8:9], v[8:9], 0, v[80:81]
	s_addc_u32 s3, s19, s3
	v_lshl_add_u64 v[8:9], s[2:3], 0, v[8:9]
	s_mov_b64 s[2:3], 0x3c0c000
	v_mul_lo_u32 v11, v86, s77
	v_lshlrev_b32_e32 v10, 5, v10
	v_lshl_add_u64 v[8:9], v[8:9], 0, s[2:3]
	v_add3_u32 v10, v11, v10, s50
	s_mov_b32 s0, 0

.LBB0_1112:
	s_cmp_lg_u32 s16, 6
	s_cbranch_scc1 .LBB0_1135
	s_cmp_lg_u32 s58, 13
	s_waitcnt vmcnt(0) lgkmcnt(0)
	s_barrier
	s_cbranch_scc1 .LBB0_1134
	s_lshl_b32 s0, s17, 2
	v_readlane_b32 s2, v254, 10
	s_add_i32 s8, s0, s2
	v_readlane_b32 s0, v255, 10
	s_add_i32 s2, 0, 0x21000
	v_and_b32_e32 v0, -16, v194
	v_mov_b32_e32 v7, s0
	s_movk_i32 s0, 0x80
	v_bitop3_b32 v1, v195, s0, v7 bitop3:0x36
	v_lshl_add_u32 v1, v1, 2, s2
	ds_read_b32 v1, v1
	v_add_u32_e32 v6, s7, v0
	v_add_u32_e32 v84, s97, v0
	v_or_b32_e32 v0, v195, v206
	v_lshlrev_b32_e32 v82, 2, v0
	s_waitcnt lgkmcnt(0)
	v_add_f32_e32 v0, v8, v1
	v_fmamk_f32 v0, v0, 0x3c000000, v180
	v_mul_f32_e32 v1, 0x4b800000, v0
	v_cmp_gt_f32_e32 vcc, s66, v0
	ds_bpermute_b32 v4, v82, v193
	v_mad_u32_u24 v80, v195, s77, v84
	v_cndmask_b32_e32 v0, v0, v1, vcc
	v_rsq_f32_e32 v5, v0
	ds_read_b128 v[0:3], v6
	ds_read_b128 v[152:155], v6 offset:64
	ds_read_b128 v[156:159], v6 offset:128
	ds_read_b128 v[160:163], v6 offset:192
	ds_read_b128 v[164:167], v6 offset:256
	s_movk_i32 s0, 0x90
	v_mul_f32_e32 v8, 0x45800000, v5
	v_cndmask_b32_e32 v8, v5, v8, vcc
	s_waitcnt lgkmcnt(4)
	v_pk_fma_f32 v[2:3], v[150:151], v[4:5], v[2:3] op_sel_hi:[1,0,1]
	v_pk_fma_f32 v[0:1], v[148:149], v[4:5], v[0:1] op_sel_hi:[1,0,1]
	v_pk_mul_f32 v[148:149], v[2:3], v[8:9] op_sel_hi:[1,0]
	v_pk_mul_f32 v[86:87], v[0:1], v[8:9] op_sel_hi:[1,0]
	ds_read_b128 v[0:3], v6 offset:320
	s_waitcnt lgkmcnt(4)
	v_pk_fma_f32 v[144:145], v[144:145], v[4:5], v[152:153] op_sel_hi:[1,0,1]
	s_waitcnt lgkmcnt(1)
	v_pk_mul_f32 v[150:151], v[166:167], v[148:149]
	v_pk_mul_f32 v[144:145], v[144:145], v[8:9] op_sel_hi:[1,0]
	v_pk_mul_f32 v[148:149], v[164:165], v[86:87]
	v_pk_fma_f32 v[86:87], v[146:147], v[4:5], v[154:155] op_sel_hi:[1,0,1]
	s_waitcnt lgkmcnt(0)
	v_pk_mul_f32 v[0:1], v[0:1], v[144:145]
	ds_read_b128 v[144:147], v6 offset:384
	v_pk_mul_f32 v[86:87], v[86:87], v[8:9] op_sel_hi:[1,0]
	v_pk_fma_f32 v[140:141], v[140:141], v[4:5], v[156:157] op_sel_hi:[1,0,1]
	v_pk_mul_f32 v[2:3], v[2:3], v[86:87]
	v_pk_fma_f32 v[86:87], v[142:143], v[4:5], v[158:159] op_sel_hi:[1,0,1]
	v_pk_mul_f32 v[152:153], v[140:141], v[8:9] op_sel_hi:[1,0]
	ds_read_b128 v[140:143], v6 offset:448
	v_pk_mul_f32 v[86:87], v[86:87], v[8:9] op_sel_hi:[1,0]
	s_waitcnt lgkmcnt(1)
	v_pk_mul_f32 v[144:145], v[144:145], v[152:153]
	v_pk_mul_f32 v[146:147], v[146:147], v[86:87]
	v_pk_fma_f32 v[86:87], v[138:139], v[4:5], v[162:163] op_sel_hi:[1,0,1]
	v_pk_fma_f32 v[4:5], v[136:137], v[4:5], v[160:161] op_sel_hi:[1,0,1]
	v_pk_mul_f32 v[86:87], v[86:87], v[8:9] op_sel_hi:[1,0]
	v_pk_mul_f32 v[4:5], v[4:5], v[8:9] op_sel_hi:[1,0]
	s_waitcnt lgkmcnt(0)
	v_pk_mul_f32 v[138:139], v[142:143], v[86:87]
	v_pk_mul_f32 v[136:137], v[140:141], v[4:5]
	ds_write_b128 v80, v[148:151]
	ds_write_b128 v80, v[0:3] offset:64
	ds_write_b128 v80, v[144:147] offset:128
	ds_write_b128 v80, v[136:139] offset:192
	v_bitop3_b32 v0, v195, s0, v7 bitop3:0x36
	v_lshl_add_u32 v0, v0, 2, s2
	s_nop 1
	ds_read_b32 v4, v0
	ds_read_b128 v[0:3], v6 offset:64
	ds_read_b128 v[136:139], v6
	ds_read_b128 v[140:143], v6 offset:192
	ds_read_b128 v[144:147], v6 offset:128
	ds_read_b128 v[148:151], v6 offset:256
	v_readlane_b32 s26, v254, 37
	s_waitcnt lgkmcnt(5)
	v_add_f32_e32 v4, v9, v4
	v_fmamk_f32 v4, v4, 0x3c000000, v180
	v_mul_f32_e32 v5, 0x4b800000, v4
	v_cmp_gt_f32_e32 vcc, s66, v4
	v_readlane_b32 s27, v254, 38
	s_ashr_i32 s9, s8, 31
	v_cndmask_b32_e32 v4, v4, v5, vcc
	v_rsq_f32_e32 v5, v4
	ds_bpermute_b32 v4, v82, v193 offset:64
	s_lshl_b64 s[8:9], s[8:9], 17
	v_ashrrev_i32_e32 v173, 31, v172
	v_mul_f32_e32 v7, 0x45800000, v5
	v_cndmask_b32_e32 v8, v5, v7, vcc
	s_waitcnt lgkmcnt(0)
	v_pk_fma_f32 v[132:133], v[132:133], v[4:5], v[136:137] op_sel_hi:[1,0,1]
	v_pk_fma_f32 v[86:87], v[134:135], v[4:5], v[138:139] op_sel_hi:[1,0,1]
	v_pk_mul_f32 v[136:137], v[132:133], v[8:9] op_sel_hi:[1,0]
	ds_read_b128 v[132:135], v6 offset:320
	v_pk_fma_f32 v[2:3], v[130:131], v[4:5], v[2:3] op_sel_hi:[1,0,1]
	v_pk_fma_f32 v[0:1], v[128:129], v[4:5], v[0:1] op_sel_hi:[1,0,1]
	ds_read_b128 v[128:131], v6 offset:384
	v_pk_mul_f32 v[86:87], v[86:87], v[8:9] op_sel_hi:[1,0]
	v_pk_mul_f32 v[0:1], v[0:1], v[8:9] op_sel_hi:[1,0]
	v_pk_fma_f32 v[124:125], v[124:125], v[4:5], v[144:145] op_sel_hi:[1,0,1]
	v_pk_mul_f32 v[138:139], v[150:151], v[86:87]
	s_waitcnt lgkmcnt(1)
	v_pk_mul_f32 v[0:1], v[132:133], v[0:1]
	v_pk_fma_f32 v[86:87], v[126:127], v[4:5], v[146:147] op_sel_hi:[1,0,1]
	v_pk_mul_f32 v[132:133], v[124:125], v[8:9] op_sel_hi:[1,0]
	ds_read_b128 v[124:127], v6 offset:448
	v_pk_mul_f32 v[86:87], v[86:87], v[8:9] op_sel_hi:[1,0]
	v_pk_mul_f32 v[136:137], v[148:149], v[136:137]
	s_waitcnt lgkmcnt(1)
	v_pk_mul_f32 v[130:131], v[130:131], v[86:87]
	v_pk_fma_f32 v[86:87], v[122:123], v[4:5], v[142:143] op_sel_hi:[1,0,1]
	v_pk_fma_f32 v[4:5], v[120:121], v[4:5], v[140:141] op_sel_hi:[1,0,1]
	v_pk_mul_f32 v[2:3], v[2:3], v[8:9] op_sel_hi:[1,0]
	v_pk_mul_f32 v[4:5], v[4:5], v[8:9] op_sel_hi:[1,0]
	v_pk_mul_f32 v[8:9], v[86:87], v[8:9] op_sel_hi:[1,0]
	v_pk_mul_f32 v[2:3], v[134:135], v[2:3]
	v_pk_mul_f32 v[128:129], v[128:129], v[132:133]
	s_waitcnt lgkmcnt(0)
	v_pk_mul_f32 v[122:123], v[126:127], v[8:9]
	v_pk_mul_f32 v[120:121], v[124:125], v[4:5]
	ds_write_b128 v80, v[136:139] offset:4352
	ds_write_b128 v80, v[0:3] offset:4416
	ds_write_b128 v80, v[128:131] offset:4480
	ds_write_b128 v80, v[120:123] offset:4544
	s_nop 1
	v_cndmask_b32_e64 v0, 0, 1, s[26:27]
	v_cmp_ne_u32_e64 s[40:41], 1, v0
	v_lshlrev_b32_e32 v0, 4, v194
	s_andn2_b64 vcc, exec, s[26:27]
	v_mul_lo_u32 v8, v172, s77
	v_and_b32_e32 v0, 0xf0, v0
	v_readlane_b32 s3, v254, 11
	s_cbranch_vccnz .LBB0_1117
	v_readlane_b32 s0, v254, 16
	v_lshlrev_b64 v[2:3], 9, v[172:173]
	s_add_u32 s26, s42, s0
	v_lshl_add_u64 v[2:3], s[8:9], 0, v[2:3]
	v_mov_b32_e32 v1, v81
	s_addc_u32 s27, s43, 0
	v_lshl_add_u64 v[2:3], v[2:3], 0, v[0:1]
	v_lshl_add_u64 v[2:3], s[26:27], 0, v[2:3]
	s_mov_b64 s[26:27], 0x3800000
	v_lshl_add_u64 v[2:3], v[2:3], 0, s[26:27]
	v_add3_u32 v1, v8, v0, s97
	s_mov_b32 s0, 0

.LBB0_1118:
	v_add_u32_e32 v85, -16, v80
	ds_read_b128 v[120:123], v85
	ds_read_b128 v[124:127], v80
	v_lshl_add_u64 v[86:87], v[4:5], 0, s[26:27]
	s_add_u32 s26, s26, 0x800
	s_addc_u32 s27, s27, 0
	s_waitcnt lgkmcnt(1)
	v_cvt_pk_bf16_f32 v120, v120, v121
	v_cvt_pk_bf16_f32 v121, v122, v123
	s_waitcnt lgkmcnt(0)
	v_cvt_pk_bf16_f32 v122, v124, v125
	v_cvt_pk_bf16_f32 v123, v126, v127
	global_store_dwordx4 v[86:87], v[120:123], off sc1
	s_nop 1
	v_add_u32_e32 v80, 0x880, v80
	s_cmpk_lg_i32 s26, 0x2000
	s_cbranch_scc1 .LBB0_1118
	v_xor_b32_e32 v4, 0xa0, v9
	v_lshl_add_u32 v4, v4, 2, s2
	ds_read_b32 v5, v4
	ds_bpermute_b32 v4, v82, v193 offset:128
	ds_read_b128 v[120:123], v6
	ds_read_b128 v[124:127], v6 offset:64
	ds_read_b128 v[128:131], v6 offset:128
	ds_read_b128 v[132:135], v6 offset:192
	ds_read_b128 v[136:139], v6 offset:256
	s_waitcnt lgkmcnt(6)
	v_add_f32_e32 v5, v10, v5
	v_fmamk_f32 v5, v5, 0x3c000000, v180
	v_mul_f32_e32 v10, 0x4b800000, v5
	v_cmp_gt_f32_e32 vcc, s66, v5
	s_nop 1
	v_cndmask_b32_e32 v5, v5, v10, vcc
	v_rsq_f32_e32 v5, v5
	s_nop 0
	v_mul_f32_e32 v10, 0x45800000, v5
	v_cndmask_b32_e32 v10, v5, v10, vcc
	s_waitcnt lgkmcnt(4)
	v_pk_fma_f32 v[116:117], v[116:117], v[4:5], v[120:121] op_sel_hi:[1,0,1]
	v_pk_fma_f32 v[86:87], v[118:119], v[4:5], v[122:123] op_sel_hi:[1,0,1]
	v_pk_mul_f32 v[120:121], v[116:117], v[10:11] op_sel_hi:[1,0]
	ds_read_b128 v[116:119], v6 offset:320
	v_pk_mul_f32 v[86:87], v[86:87], v[10:11] op_sel_hi:[1,0]
	s_waitcnt lgkmcnt(4)
	v_pk_fma_f32 v[112:113], v[112:113], v[4:5], v[124:125] op_sel_hi:[1,0,1]
	s_waitcnt lgkmcnt(1)
	v_pk_mul_f32 v[122:123], v[138:139], v[86:87]
	v_pk_fma_f32 v[86:87], v[114:115], v[4:5], v[126:127] op_sel_hi:[1,0,1]
	v_pk_mul_f32 v[112:113], v[112:113], v[10:11] op_sel_hi:[1,0]
	v_pk_mul_f32 v[86:87], v[86:87], v[10:11] op_sel_hi:[1,0]
	s_waitcnt lgkmcnt(0)
	v_pk_mul_f32 v[112:113], v[116:117], v[112:113]
	v_pk_mul_f32 v[114:115], v[118:119], v[86:87]
	ds_read_b128 v[116:119], v6 offset:384
	v_pk_fma_f32 v[108:109], v[108:109], v[4:5], v[128:129] op_sel_hi:[1,0,1]
	v_pk_fma_f32 v[86:87], v[110:111], v[4:5], v[130:131] op_sel_hi:[1,0,1]
	v_pk_mul_f32 v[124:125], v[108:109], v[10:11] op_sel_hi:[1,0]
	ds_read_b128 v[108:111], v6 offset:448
	v_pk_mul_f32 v[86:87], v[86:87], v[10:11] op_sel_hi:[1,0]
	v_pk_mul_f32 v[120:121], v[136:137], v[120:121]
	s_waitcnt lgkmcnt(1)
	v_pk_mul_f32 v[118:119], v[118:119], v[86:87]
	v_pk_fma_f32 v[86:87], v[106:107], v[4:5], v[134:135] op_sel_hi:[1,0,1]
	v_pk_fma_f32 v[4:5], v[104:105], v[4:5], v[132:133] op_sel_hi:[1,0,1]
	v_pk_mul_f32 v[86:87], v[86:87], v[10:11] op_sel_hi:[1,0]
	v_pk_mul_f32 v[4:5], v[4:5], v[10:11] op_sel_hi:[1,0]
	v_add_u32_e32 v10, v84, v1
	v_xor_b32_e32 v1, 0xb0, v9
	v_pk_mul_f32 v[116:117], v[116:117], v[124:125]
	s_waitcnt lgkmcnt(0)
	v_pk_mul_f32 v[106:107], v[110:111], v[86:87]
	v_pk_mul_f32 v[104:105], v[108:109], v[4:5]
	ds_write_b128 v10, v[120:123]
	ds_write_b128 v10, v[112:115] offset:64
	ds_write_b128 v10, v[116:119] offset:128
	ds_write_b128 v10, v[104:107] offset:192
	v_lshl_add_u32 v1, v1, 2, s2
	s_nop 1
	ds_read_b32 v1, v1
	ds_read_b128 v[84:87], v6 offset:64
	ds_read_b128 v[104:107], v6
	ds_read_b128 v[108:111], v6 offset:192
	ds_read_b128 v[112:115], v6 offset:128
	ds_read_b128 v[116:119], v6 offset:256
	s_waitcnt lgkmcnt(5)
	v_add_f32_e32 v1, v11, v1
	v_fmamk_f32 v1, v1, 0x3c000000, v180
	v_mul_f32_e32 v4, 0x4b800000, v1
	v_cmp_gt_f32_e32 vcc, s66, v1
	s_nop 1
	v_cndmask_b32_e32 v1, v1, v4, vcc
	v_rsq_f32_e32 v1, v1
	ds_bpermute_b32 v4, v82, v193 offset:192
	v_mul_f32_e32 v5, 0x45800000, v1
	v_cndmask_b32_e32 v80, v1, v5, vcc
	s_waitcnt lgkmcnt(0)
	v_pk_fma_f32 v[102:103], v[102:103], v[4:5], v[106:107] op_sel_hi:[1,0,1]
	v_pk_fma_f32 v[100:101], v[100:101], v[4:5], v[104:105] op_sel_hi:[1,0,1]
	v_pk_mul_f32 v[106:107], v[102:103], v[80:81] op_sel_hi:[1,0]
	v_pk_mul_f32 v[104:105], v[100:101], v[80:81] op_sel_hi:[1,0]
	ds_read_b128 v[100:103], v6 offset:320
	v_pk_fma_f32 v[86:87], v[98:99], v[4:5], v[86:87] op_sel_hi:[1,0,1]
	v_pk_fma_f32 v[84:85], v[96:97], v[4:5], v[84:85] op_sel_hi:[1,0,1]
	v_pk_mul_f32 v[86:87], v[86:87], v[80:81] op_sel_hi:[1,0]
	v_pk_mul_f32 v[84:85], v[84:85], v[80:81] op_sel_hi:[1,0]
	v_pk_fma_f32 v[94:95], v[94:95], v[4:5], v[114:115] op_sel_hi:[1,0,1]
	v_pk_fma_f32 v[92:93], v[92:93], v[4:5], v[112:113] op_sel_hi:[1,0,1]
	s_waitcnt lgkmcnt(0)
	v_pk_mul_f32 v[86:87], v[102:103], v[86:87]
	v_pk_mul_f32 v[84:85], v[100:101], v[84:85]
	ds_read_b128 v[96:99], v6 offset:384
	v_pk_mul_f32 v[100:101], v[92:93], v[80:81] op_sel_hi:[1,0]
	v_pk_mul_f32 v[102:103], v[94:95], v[80:81] op_sel_hi:[1,0]
	ds_read_b128 v[92:95], v6 offset:448
	v_pk_fma_f32 v[90:91], v[90:91], v[4:5], v[110:111] op_sel_hi:[1,0,1]
	v_pk_fma_f32 v[4:5], v[88:89], v[4:5], v[108:109] op_sel_hi:[1,0,1]
	v_pk_mul_f32 v[106:107], v[118:119], v[106:107]
	v_pk_mul_f32 v[104:105], v[116:117], v[104:105]
	v_pk_mul_f32 v[4:5], v[4:5], v[80:81] op_sel_hi:[1,0]
	v_pk_mul_f32 v[88:89], v[90:91], v[80:81] op_sel_hi:[1,0]
	s_waitcnt lgkmcnt(1)
	v_pk_mul_f32 v[98:99], v[98:99], v[102:103]
	v_pk_mul_f32 v[96:97], v[96:97], v[100:101]
	s_waitcnt lgkmcnt(0)
	v_pk_mul_f32 v[90:91], v[94:95], v[88:89]
	v_pk_mul_f32 v[88:89], v[92:93], v[4:5]
	ds_write_b128 v10, v[104:107] offset:4352
	ds_write_b128 v10, v[84:87] offset:4416
	ds_write_b128 v10, v[96:99] offset:4480
	ds_write_b128 v10, v[88:91] offset:4544
	s_nop 1
	s_and_b64 vcc, exec, s[40:41]
	s_cbranch_vccnz .LBB0_1122
	v_readlane_b32 s0, v254, 52
	s_add_i32 s0, s0, s64
	s_lshl_b32 s0, s0, 9
	s_and_b32 s0, s0, 0x1c000
	v_readlane_b32 s3, v254, 57
	s_add_u32 s26, s42, s3
	s_addc_u32 s27, s43, 0
	s_add_u32 s28, s8, s0
	s_addc_u32 s29, s9, 0
	v_lshlrev_b64 v[4:5], 9, v[172:173]
	v_lshl_add_u64 v[4:5], s[28:29], 0, v[4:5]
	v_mov_b32_e32 v1, v81
	v_lshl_add_u64 v[4:5], v[4:5], 0, v[0:1]
	v_lshl_add_u64 v[4:5], s[26:27], 0, v[4:5]
	s_mov_b64 s[26:27], 0x3800000
	v_lshl_add_u64 v[4:5], v[4:5], 0, s[26:27]
	v_add3_u32 v1, v8, v0, s97
	s_mov_b32 s0, 0

.LBB0_1123:
	v_add_u32_e32 v84, -16, v1
	ds_read_b128 v[84:87], v84
	ds_read_b128 v[88:91], v1
	v_add_u32_e32 v1, 0x880, v1
	s_waitcnt lgkmcnt(1)
	v_cvt_pk_bf16_f32 v84, v84, v85
	v_cvt_pk_bf16_f32 v85, v86, v87
	s_waitcnt lgkmcnt(0)
	v_cvt_pk_bf16_f32 v86, v88, v89
	v_cvt_pk_bf16_f32 v87, v90, v91
	v_lshl_add_u64 v[88:89], v[4:5], 0, s[26:27]
	global_store_dwordx4 v[88:89], v[84:87], off sc1
	s_nop 1
	s_add_u32 s26, s26, 0x800
	s_addc_u32 s27, s27, 0
	s_cmpk_lg_i32 s26, 0x2000
	s_cbranch_scc1 .LBB0_1123
	v_xor_b32_e32 v1, 0xc0, v9
	v_lshl_add_u32 v1, v1, 2, s2
	ds_read_b32 v1, v1
	ds_bpermute_b32 v4, v82, v192
	ds_read_b128 v[84:87], v6
	ds_read_b128 v[88:91], v6 offset:64
	ds_read_b128 v[92:95], v6 offset:128
	ds_read_b128 v[96:99], v6 offset:192
	ds_read_b128 v[100:103], v6 offset:256
	s_waitcnt lgkmcnt(6)
	v_add_f32_e32 v1, v12, v1
	v_fmamk_f32 v1, v1, 0x3c000000, v180
	v_mul_f32_e32 v5, 0x4b800000, v1
	v_cmp_gt_f32_e32 vcc, s66, v1
	s_nop 1
	v_cndmask_b32_e32 v1, v1, v5, vcc
	v_rsq_f32_e32 v1, v1
	s_nop 0
	v_mul_f32_e32 v5, 0x45800000, v1
	v_cndmask_b32_e32 v12, v1, v5, vcc
	s_waitcnt lgkmcnt(4)
	v_pk_fma_f32 v[78:79], v[78:79], v[4:5], v[86:87] op_sel_hi:[1,0,1]
	v_pk_fma_f32 v[76:77], v[76:77], v[4:5], v[84:85] op_sel_hi:[1,0,1]
	v_pk_mul_f32 v[86:87], v[78:79], v[12:13] op_sel_hi:[1,0]
	v_pk_mul_f32 v[84:85], v[76:77], v[12:13] op_sel_hi:[1,0]
	ds_read_b128 v[76:79], v6 offset:320
	s_waitcnt lgkmcnt(4)
	v_pk_fma_f32 v[74:75], v[74:75], v[4:5], v[90:91] op_sel_hi:[1,0,1]
	v_pk_fma_f32 v[72:73], v[72:73], v[4:5], v[88:89] op_sel_hi:[1,0,1]
	v_pk_mul_f32 v[74:75], v[74:75], v[12:13] op_sel_hi:[1,0]
	v_pk_mul_f32 v[72:73], v[72:73], v[12:13] op_sel_hi:[1,0]
	s_waitcnt lgkmcnt(3)
	v_pk_fma_f32 v[70:71], v[70:71], v[4:5], v[94:95] op_sel_hi:[1,0,1]
	v_pk_fma_f32 v[68:69], v[68:69], v[4:5], v[92:93] op_sel_hi:[1,0,1]
	v_pk_mul_f32 v[90:91], v[70:71], v[12:13] op_sel_hi:[1,0]
	v_pk_mul_f32 v[88:89], v[68:69], v[12:13] op_sel_hi:[1,0]
	ds_read_b128 v[68:71], v6 offset:448
	s_waitcnt lgkmcnt(1)
	v_pk_mul_f32 v[74:75], v[78:79], v[74:75]
	v_pk_mul_f32 v[72:73], v[76:77], v[72:73]
	ds_read_b128 v[76:79], v6 offset:384
	v_pk_fma_f32 v[66:67], v[66:67], v[4:5], v[98:99] op_sel_hi:[1,0,1]
	v_pk_fma_f32 v[4:5], v[64:65], v[4:5], v[96:97] op_sel_hi:[1,0,1]
	v_pk_mul_f32 v[86:87], v[102:103], v[86:87]
	v_pk_mul_f32 v[84:85], v[100:101], v[84:85]
	v_pk_mul_f32 v[4:5], v[4:5], v[12:13] op_sel_hi:[1,0]
	v_pk_mul_f32 v[64:65], v[66:67], v[12:13] op_sel_hi:[1,0]
	v_xor_b32_e32 v1, 0xd0, v9
	s_waitcnt lgkmcnt(0)
	v_pk_mul_f32 v[78:79], v[78:79], v[90:91]
	v_pk_mul_f32 v[76:77], v[76:77], v[88:89]
	v_pk_mul_f32 v[66:67], v[70:71], v[64:65]
	v_pk_mul_f32 v[64:65], v[68:69], v[4:5]
	ds_write_b128 v10, v[84:87]
	ds_write_b128 v10, v[72:75] offset:64
	ds_write_b128 v10, v[76:79] offset:128
	ds_write_b128 v10, v[64:67] offset:192
	v_lshl_add_u32 v1, v1, 2, s2
	s_nop 1
	ds_read_b32 v1, v1
	ds_read_b128 v[64:67], v6 offset:64
	ds_read_b128 v[68:71], v6
	ds_read_b128 v[72:75], v6 offset:192
	ds_read_b128 v[76:79], v6 offset:128
	s_waitcnt lgkmcnt(4)
	v_add_f32_e32 v1, v13, v1
	v_fmamk_f32 v1, v1, 0x3c000000, v180
	v_mul_f32_e32 v4, 0x4b800000, v1
	v_cmp_gt_f32_e32 vcc, s66, v1
	s_nop 1
	v_cndmask_b32_e32 v1, v1, v4, vcc
	v_rsq_f32_e32 v1, v1
	ds_bpermute_b32 v4, v83, v192
	ds_read_b128 v[82:85], v6 offset:256
	v_mul_f32_e32 v5, 0x45800000, v1
	v_cndmask_b32_e32 v12, v1, v5, vcc
	s_waitcnt lgkmcnt(1)
	v_pk_fma_f32 v[62:63], v[62:63], v[4:5], v[70:71] op_sel_hi:[1,0,1]
	v_pk_fma_f32 v[60:61], v[60:61], v[4:5], v[68:69] op_sel_hi:[1,0,1]
	v_pk_mul_f32 v[70:71], v[62:63], v[12:13] op_sel_hi:[1,0]
	v_pk_mul_f32 v[68:69], v[60:61], v[12:13] op_sel_hi:[1,0]
	ds_read_b128 v[60:63], v6 offset:320
	v_pk_fma_f32 v[58:59], v[58:59], v[4:5], v[66:67] op_sel_hi:[1,0,1]
	v_pk_fma_f32 v[56:57], v[56:57], v[4:5], v[64:65] op_sel_hi:[1,0,1]
	v_pk_mul_f32 v[58:59], v[58:59], v[12:13] op_sel_hi:[1,0]
	v_pk_mul_f32 v[56:57], v[56:57], v[12:13] op_sel_hi:[1,0]
	v_pk_fma_f32 v[54:55], v[54:55], v[4:5], v[78:79] op_sel_hi:[1,0,1]
	v_pk_fma_f32 v[52:53], v[52:53], v[4:5], v[76:77] op_sel_hi:[1,0,1]
	s_waitcnt lgkmcnt(0)
	v_pk_mul_f32 v[58:59], v[62:63], v[58:59]
	v_pk_mul_f32 v[56:57], v[60:61], v[56:57]
	ds_read_b128 v[60:63], v6 offset:384
	v_pk_mul_f32 v[64:65], v[52:53], v[12:13] op_sel_hi:[1,0]
	v_pk_mul_f32 v[66:67], v[54:55], v[12:13] op_sel_hi:[1,0]
	ds_read_b128 v[52:55], v6 offset:448
	v_pk_fma_f32 v[50:51], v[50:51], v[4:5], v[74:75] op_sel_hi:[1,0,1]
	v_pk_fma_f32 v[4:5], v[48:49], v[4:5], v[72:73] op_sel_hi:[1,0,1]
	v_pk_mul_f32 v[70:71], v[84:85], v[70:71]
	v_pk_mul_f32 v[68:69], v[82:83], v[68:69]
	v_pk_mul_f32 v[4:5], v[4:5], v[12:13] op_sel_hi:[1,0]
	v_pk_mul_f32 v[12:13], v[50:51], v[12:13] op_sel_hi:[1,0]
	s_waitcnt lgkmcnt(1)
	v_pk_mul_f32 v[62:63], v[62:63], v[66:67]
	v_pk_mul_f32 v[60:61], v[60:61], v[64:65]
	s_waitcnt lgkmcnt(0)
	v_pk_mul_f32 v[50:51], v[54:55], v[12:13]
	v_pk_mul_f32 v[48:49], v[52:53], v[4:5]
	ds_write_b128 v10, v[68:71] offset:4352
	ds_write_b128 v10, v[56:59] offset:4416
	ds_write_b128 v10, v[60:63] offset:4480
	ds_write_b128 v10, v[48:51] offset:4544
	s_nop 1
	s_and_b64 vcc, exec, s[40:41]
	s_cbranch_vccnz .LBB0_1127
	v_readlane_b32 s0, v254, 53
	s_add_i32 s0, s0, s64
	s_lshl_b32 s0, s0, 9
	s_and_b32 s0, s0, 0x18000
	v_readlane_b32 s3, v254, 57
	s_add_u32 s26, s42, s3
	s_addc_u32 s27, s43, 0
	s_add_u32 s28, s8, s0
	s_addc_u32 s29, s9, 0
	v_lshlrev_b64 v[4:5], 9, v[172:173]
	v_lshl_add_u64 v[4:5], s[28:29], 0, v[4:5]
	v_mov_b32_e32 v1, v81
	v_lshl_add_u64 v[4:5], v[4:5], 0, v[0:1]
	v_lshl_add_u64 v[4:5], s[26:27], 0, v[4:5]
	s_mov_b64 s[26:27], 0x3800000
	v_lshl_add_u64 v[4:5], v[4:5], 0, s[26:27]
	v_add3_u32 v1, v8, v0, s97
	s_mov_b32 s0, 0

.LBB0_1128:
	v_add_u32_e32 v12, -16, v1
	ds_read_b128 v[48:51], v12
	ds_read_b128 v[52:55], v1
	v_lshl_add_u64 v[12:13], v[4:5], 0, s[26:27]
	s_add_u32 s26, s26, 0x800
	s_addc_u32 s27, s27, 0
	s_waitcnt lgkmcnt(1)
	v_cvt_pk_bf16_f32 v48, v48, v49
	v_cvt_pk_bf16_f32 v49, v50, v51
	s_waitcnt lgkmcnt(0)
	v_cvt_pk_bf16_f32 v50, v52, v53
	v_cvt_pk_bf16_f32 v51, v54, v55
	global_store_dwordx4 v[12:13], v[48:51], off sc1
	s_nop 1
	v_add_u32_e32 v1, 0x880, v1
	s_cmpk_lg_i32 s26, 0x2000
	s_cbranch_scc1 .LBB0_1128
	v_xor_b32_e32 v1, 0xe0, v9
	v_lshl_add_u32 v1, v1, 2, s2
	ds_read_b32 v1, v1
	ds_bpermute_b32 v4, v80, v192
	ds_read_b128 v[48:51], v6
	ds_read_b128 v[52:55], v6 offset:64
	ds_read_b128 v[56:59], v6 offset:128
	ds_read_b128 v[60:63], v6 offset:192
	ds_read_b128 v[64:67], v6 offset:256
	s_waitcnt lgkmcnt(6)
	v_add_f32_e32 v1, v14, v1
	v_fmamk_f32 v1, v1, 0x3c000000, v180
	v_mul_f32_e32 v5, 0x4b800000, v1
	v_cmp_gt_f32_e32 vcc, s66, v1
	s_nop 1
	v_cndmask_b32_e32 v1, v1, v5, vcc
	v_rsq_f32_e32 v1, v1
	s_nop 0
	v_mul_f32_e32 v5, 0x45800000, v1
	v_cndmask_b32_e32 v12, v1, v5, vcc
	s_waitcnt lgkmcnt(4)
	v_pk_fma_f32 v[46:47], v[46:47], v[4:5], v[50:51] op_sel_hi:[1,0,1]
	v_pk_fma_f32 v[44:45], v[44:45], v[4:5], v[48:49] op_sel_hi:[1,0,1]
	v_pk_mul_f32 v[50:51], v[46:47], v[12:13] op_sel_hi:[1,0]
	v_pk_mul_f32 v[48:49], v[44:45], v[12:13] op_sel_hi:[1,0]
	ds_read_b128 v[44:47], v6 offset:320
	s_waitcnt lgkmcnt(4)
	v_pk_fma_f32 v[42:43], v[42:43], v[4:5], v[54:55] op_sel_hi:[1,0,1]
	v_pk_fma_f32 v[40:41], v[40:41], v[4:5], v[52:53] op_sel_hi:[1,0,1]
	v_pk_mul_f32 v[42:43], v[42:43], v[12:13] op_sel_hi:[1,0]
	v_pk_mul_f32 v[40:41], v[40:41], v[12:13] op_sel_hi:[1,0]
	s_waitcnt lgkmcnt(3)
	v_pk_fma_f32 v[38:39], v[38:39], v[4:5], v[58:59] op_sel_hi:[1,0,1]
	v_pk_fma_f32 v[36:37], v[36:37], v[4:5], v[56:57] op_sel_hi:[1,0,1]
	v_pk_mul_f32 v[54:55], v[38:39], v[12:13] op_sel_hi:[1,0]
	v_pk_mul_f32 v[52:53], v[36:37], v[12:13] op_sel_hi:[1,0]
	ds_read_b128 v[36:39], v6 offset:448
	s_waitcnt lgkmcnt(1)
	v_pk_mul_f32 v[42:43], v[46:47], v[42:43]
	v_pk_mul_f32 v[40:41], v[44:45], v[40:41]
	ds_read_b128 v[44:47], v6 offset:384
	v_pk_fma_f32 v[34:35], v[34:35], v[4:5], v[62:63] op_sel_hi:[1,0,1]
	v_pk_fma_f32 v[4:5], v[32:33], v[4:5], v[60:61] op_sel_hi:[1,0,1]
	v_pk_mul_f32 v[50:51], v[66:67], v[50:51]
	v_pk_mul_f32 v[48:49], v[64:65], v[48:49]
	v_pk_mul_f32 v[4:5], v[4:5], v[12:13] op_sel_hi:[1,0]
	v_pk_mul_f32 v[12:13], v[34:35], v[12:13] op_sel_hi:[1,0]
	v_xor_b32_e32 v1, 0xf0, v9
	s_waitcnt lgkmcnt(0)
	v_pk_mul_f32 v[46:47], v[46:47], v[54:55]
	v_pk_mul_f32 v[44:45], v[44:45], v[52:53]
	v_pk_mul_f32 v[34:35], v[38:39], v[12:13]
	v_pk_mul_f32 v[32:33], v[36:37], v[4:5]
	ds_write_b128 v10, v[48:51]
	ds_write_b128 v10, v[40:43] offset:64
	ds_write_b128 v10, v[44:47] offset:128
	ds_write_b128 v10, v[32:35] offset:192
	v_lshl_add_u32 v1, v1, 2, s2
	s_nop 1
	ds_read_b32 v1, v1
	ds_read_b128 v[32:35], v6 offset:64
	ds_read_b128 v[36:39], v6
	s_waitcnt lgkmcnt(2)
	v_add_f32_e32 v1, v15, v1
	v_fmamk_f32 v1, v1, 0x3c000000, v180
	v_mul_f32_e32 v4, 0x4b800000, v1
	v_cmp_gt_f32_e32 vcc, s66, v1
	ds_read_b128 v[12:15], v6 offset:192
	ds_read_b128 v[40:43], v6 offset:128
	v_cndmask_b32_e32 v1, v1, v4, vcc
	v_rsq_f32_e32 v1, v1
	ds_bpermute_b32 v4, v11, v192
	ds_read_b128 v[44:47], v6 offset:256
	v_mul_f32_e32 v5, 0x45800000, v1
	v_cndmask_b32_e32 v48, v1, v5, vcc
	s_waitcnt lgkmcnt(1)
	v_pk_fma_f32 v[30:31], v[30:31], v[4:5], v[38:39] op_sel_hi:[1,0,1]
	v_pk_fma_f32 v[28:29], v[28:29], v[4:5], v[36:37] op_sel_hi:[1,0,1]
	v_pk_mul_f32 v[38:39], v[30:31], v[48:49] op_sel_hi:[1,0]
	v_pk_mul_f32 v[36:37], v[28:29], v[48:49] op_sel_hi:[1,0]
	ds_read_b128 v[28:31], v6 offset:320
	v_pk_fma_f32 v[26:27], v[26:27], v[4:5], v[34:35] op_sel_hi:[1,0,1]
	v_pk_fma_f32 v[24:25], v[24:25], v[4:5], v[32:33] op_sel_hi:[1,0,1]
	v_pk_mul_f32 v[26:27], v[26:27], v[48:49] op_sel_hi:[1,0]
	v_pk_mul_f32 v[24:25], v[24:25], v[48:49] op_sel_hi:[1,0]
	v_pk_fma_f32 v[18:19], v[18:19], v[4:5], v[42:43] op_sel_hi:[1,0,1]
	v_pk_fma_f32 v[16:17], v[16:17], v[4:5], v[40:41] op_sel_hi:[1,0,1]
	s_waitcnt lgkmcnt(0)
	v_pk_mul_f32 v[26:27], v[30:31], v[26:27]
	v_pk_mul_f32 v[24:25], v[28:29], v[24:25]
	ds_read_b128 v[28:31], v6 offset:384
	v_pk_mul_f32 v[32:33], v[16:17], v[48:49] op_sel_hi:[1,0]
	v_pk_mul_f32 v[34:35], v[18:19], v[48:49] op_sel_hi:[1,0]
	ds_read_b128 v[16:19], v6 offset:448
	v_pk_fma_f32 v[14:15], v[22:23], v[4:5], v[14:15] op_sel_hi:[1,0,1]
	v_pk_fma_f32 v[4:5], v[20:21], v[4:5], v[12:13] op_sel_hi:[1,0,1]
	v_pk_mul_f32 v[38:39], v[46:47], v[38:39]
	v_pk_mul_f32 v[36:37], v[44:45], v[36:37]
	v_pk_mul_f32 v[4:5], v[4:5], v[48:49] op_sel_hi:[1,0]
	v_pk_mul_f32 v[12:13], v[14:15], v[48:49] op_sel_hi:[1,0]
	s_waitcnt lgkmcnt(1)
	v_pk_mul_f32 v[30:31], v[30:31], v[34:35]
	v_pk_mul_f32 v[28:29], v[28:29], v[32:33]
	s_waitcnt lgkmcnt(0)
	v_pk_mul_f32 v[14:15], v[18:19], v[12:13]
	v_pk_mul_f32 v[12:13], v[16:17], v[4:5]
	ds_write_b128 v10, v[36:39] offset:4352
	ds_write_b128 v10, v[24:27] offset:4416
	ds_write_b128 v10, v[28:31] offset:4480
	ds_write_b128 v10, v[12:15] offset:4544
	s_nop 1
	s_and_b64 vcc, exec, s[40:41]
	s_cbranch_vccnz .LBB0_1132
	v_readlane_b32 s0, v255, 12
	s_add_i32 s0, s0, s64
	s_lshl_b32 s0, s0, 9
	s_and_b32 s0, s0, 0x1c000
	v_readlane_b32 s2, v254, 57
	s_add_u32 s2, s42, s2
	s_addc_u32 s3, s43, 0
	s_add_u32 s8, s8, s0
	s_addc_u32 s9, s9, 0
	v_lshlrev_b64 v[4:5], 9, v[172:173]
	v_lshl_add_u64 v[4:5], s[8:9], 0, v[4:5]
	v_mov_b32_e32 v1, v81
	v_lshl_add_u64 v[4:5], v[4:5], 0, v[0:1]
	v_lshl_add_u64 v[4:5], s[2:3], 0, v[4:5]
	s_mov_b64 s[2:3], 0x3800000
	v_lshl_add_u64 v[4:5], v[4:5], 0, s[2:3]
	v_add3_u32 v0, v8, v0, s97
	s_mov_b32 s0, 0

.LBB0_1166:
	s_waitcnt vmcnt(0)
	s_and_b64 vcc, exec, s[40:41]
	s_barrier
	s_cbranch_vccnz .LBB0_1203
	v_mov_b32_e32 v70, v188
	v_readlane_b32 s40, v252, 1
	v_readlane_b32 s41, v252, 2
	v_ashrrev_i32_e32 v64, 4, v70
	s_mov_b64 s[8:9], s[40:41]
	v_cmp_lt_i32_e64 s[40:41], 1, v64
	v_lshlrev_b32_e32 v64, 2, v64
	s_mov_b64 s[28:29], s[88:89]
	v_lshl_add_u32 v65, v70, 2, s7
	v_and_b32_e32 v64, 4, v64
	ds_write_b32 v65, v86
	v_cvt_f32_ubyte0_e32 v65, v64
	v_mul_f32_e32 v65, 0xbfd49a78, v65
	v_exp_f32_e32 v65, v65
	v_and_b32_e32 v78, 15, v70
	v_and_b32_e32 v71, -16, v70
	v_or_b32_e32 v69, v78, v206
	v_mul_f32_e32 v68, 0.15915494, v65
	v_or_b32_e32 v65, 1, v64
	v_cvt_f32_ubyte0_e32 v65, v65
	v_mul_f32_e32 v65, 0xbfd49a78, v65
	v_exp_f32_e32 v65, v65
	v_add_u32_e32 v66, s7, v71
	v_lshlrev_b32_e32 v77, 2, v69
	s_nop 1
	ds_bpermute_b32 v76, v77, v85
	ds_read_b128 v[72:75], v66
	v_mul_f32_e32 v67, 0.15915494, v65
	v_or_b32_e32 v65, 2, v64
	v_or_b32_e32 v64, 3, v64
	v_cvt_f32_ubyte0_e32 v65, v65
	v_cvt_f32_ubyte0_e32 v64, v64
	v_mul_f32_e32 v65, 0xbfd49a78, v65
	v_mul_f32_e32 v64, 0xbfd49a78, v64
	v_exp_f32_e32 v65, v65
	v_exp_f32_e32 v64, v64
	s_waitcnt lgkmcnt(0)
	v_pk_fma_f32 v[60:61], v[60:61], v[76:77], v[72:73] op_sel_hi:[1,0,1]
	v_pk_fma_f32 v[62:63], v[62:63], v[76:77], v[74:75] op_sel_hi:[1,0,1]
	ds_read_b128 v[72:75], v66 offset:64
	s_cmp_gt_u32 s51, 15
	s_cselect_b64 s[18:19], -1, 0
	s_cmp_lt_u32 s51, 16
	s_cselect_b64 s[34:35], -1, 0
	s_lshl_b32 s0, s51, 8
	v_mul_f32_e32 v65, 0.15915494, v65
	v_mul_f32_e32 v64, 0.15915494, v64
	v_cvt_f32_ubyte0_e32 v69, v78
	s_add_i32 s26, s0, s95
	s_waitcnt lgkmcnt(0)
	v_pk_fma_f32 v[56:57], v[56:57], v[76:77], v[72:73] op_sel_hi:[1,0,1]
	v_pk_fma_f32 v[58:59], v[58:59], v[76:77], v[74:75] op_sel_hi:[1,0,1]
	s_and_b64 vcc, exec, s[34:35]
	v_mul_f32_e32 v76, v68, v69
	v_mul_f32_e32 v75, v67, v69
	v_mul_f32_e32 v72, v65, v69
	v_mul_f32_e32 v69, v64, v69
	v_readlane_b32 s42, v252, 3
	v_readlane_b32 s43, v252, 4
	s_cbranch_vccnz .LBB0_1169
	s_lshr_b32 s0, s26, 6
	s_and_b32 s0, s0, 14
	v_cvt_f32_ubyte0_e32 v73, s0
	v_mul_f32_e32 v74, v68, v73
	v_sin_f32_e32 v79, v74
	v_mul_f32_e32 v80, v67, v73
	ds_bpermute_b32 v86, v219, v60
	v_sin_f32_e32 v89, v80
	ds_bpermute_b32 v87, v219, v61
	v_cos_f32_e32 v82, v74
	v_sin_f32_e32 v74, v76
	v_cndmask_b32_e64 v92, -v79, v79, s[40:41]
	v_sin_f32_e32 v79, v75
	v_cndmask_b32_e64 v93, -v89, v89, s[40:41]
	s_waitcnt lgkmcnt(0)
	v_pk_mul_f32 v[86:87], v[92:93], v[86:87]
	v_cndmask_b32_e64 v92, -v74, v74, s[40:41]
	v_mul_f32_e32 v74, v65, v73
	ds_bpermute_b32 v90, v219, v56
	v_cos_f32_e32 v83, v80
	ds_bpermute_b32 v91, v219, v57
	v_cndmask_b32_e64 v93, -v79, v79, s[40:41]
	v_cos_f32_e32 v79, v74
	v_sin_f32_e32 v74, v74
	ds_bpermute_b32 v80, v219, v62
	v_mul_f32_e32 v73, v64, v73
	s_waitcnt lgkmcnt(1)
	v_pk_mul_f32 v[90:91], v[92:93], v[90:91]
	v_cndmask_b32_e64 v74, -v74, v74, s[40:41]
	ds_bpermute_b32 v95, v219, v63
	s_waitcnt lgkmcnt(1)
	v_mul_f32_e32 v92, v74, v80
	v_sin_f32_e32 v80, v73
	v_cos_f32_e32 v96, v73
	v_pk_fma_f32 v[60:61], v[82:83], v[60:61], v[86:87]
	v_sin_f32_e32 v73, v69
	ds_bpermute_b32 v83, v219, v59
	v_mul_f32_e32 v62, v79, v62
	v_cos_f32_e32 v79, v72
	v_sin_f32_e32 v93, v72
	ds_bpermute_b32 v74, v219, v58
	v_cos_f32_e32 v86, v69
	v_cos_f32_e32 v88, v76
	v_cos_f32_e32 v89, v75
	v_cndmask_b32_e64 v97, -v80, v80, s[40:41]
	v_mov_b32_e32 v94, v63
	v_cndmask_b32_e64 v87, -v73, v73, s[40:41]
	v_mov_b32_e32 v82, v59
	v_mul_f32_e32 v58, v79, v58
	v_cndmask_b32_e64 v79, -v93, v93, s[40:41]
	s_waitcnt lgkmcnt(2)
	v_pk_mul_f32 v[94:95], v[96:97], v[94:95]
	s_waitcnt lgkmcnt(1)
	v_pk_mul_f32 v[82:83], v[86:87], v[82:83]
	s_waitcnt lgkmcnt(0)
	v_mul_f32_e32 v98, v79, v74
	v_mov_b32_e32 v63, v94
	v_mov_b32_e32 v93, v95
	v_mov_b32_e32 v59, v82
	v_mov_b32_e32 v99, v83
	v_pk_add_f32 v[62:63], v[62:63], v[92:93]
	v_pk_fma_f32 v[56:57], v[88:89], v[56:57], v[90:91]
	v_pk_add_f32 v[58:59], v[58:59], v[98:99]

.LBB0_1171:
	v_mul_u32_u24_e32 v57, 0x110, v78
	s_add_i32 s0, s51, -16
	s_lshr_b32 s0, s0, 2
	v_add_u32_e32 v59, v57, v79
	s_and_b64 s[2:3], s[18:19], exec
	ds_write_b128 v59, v[48:51] offset:4352
	ds_write_b128 v59, v[52:55] offset:4416
	v_mov_b64_e32 v[48:49], s[60:61]
	s_cselect_b32 s0, s0, s51
	v_mov_b64_e32 v[50:51], s[62:63]
	s_lshl_b32 s0, s0, 2
	v_readlane_b32 s2, v254, 10
	ds_write_b128 v59, v[48:51] offset:4480
	ds_write_b128 v59, v[48:51] offset:4544
	v_readlane_b32 s3, v254, 11
	s_add_i32 s2, s0, s2
	s_nop 1
	v_cndmask_b32_e64 v48, 0, 1, s[34:35]
	s_ashr_i32 s3, s2, 31
	v_ashrrev_i32_e32 v56, 3, v70
	v_cmp_ne_u32_e64 s[42:43], 1, v48
	v_lshlrev_b32_e32 v48, 4, v70
	s_lshl_b64 s[18:19], s[2:3], 15
	s_andn2_b64 vcc, exec, s[34:35]
	v_ashrrev_i32_e32 v57, 31, v56
	v_mul_lo_u32 v58, v56, s77
	v_and_b32_e32 v50, 0x70, v48
	s_cbranch_vccnz .LBB0_1174
	v_readlane_b32 s0, v255, 23
	v_lshlrev_b64 v[48:49], 7, v[56:57]
	s_add_u32 s2, s8, s0
	v_lshl_add_u64 v[48:49], s[18:19], 0, v[48:49]
	v_mov_b32_e32 v51, v81
	s_addc_u32 s3, s9, 0
	v_lshl_add_u64 v[48:49], v[48:49], 0, v[50:51]
	v_lshl_add_u64 v[48:49], s[2:3], 0, v[48:49]
	s_mov_b64 s[2:3], 0x4000000
	v_lshl_add_u64 v[48:49], v[48:49], 0, s[2:3]
	v_add3_u32 v51, v58, v50, s97
	s_mov_b32 s0, 0

.LBB0_1393:
	s_lshl_b32 s0, s0, 8
	v_mov_b32_e32 v66, v188
	s_and_b32 s0, s0, 0x600
	s_lshl_b32 s40, s79, 8
	s_and_b32 s40, s40, 0x100
	v_and_b32_e32 v65, -16, v66
	v_and_b32_e32 v64, 15, v66
	v_add_u32_e32 v73, s78, v65
	s_add_i32 s0, s66, s0
	v_mul_u32_u24_e32 v75, 0x110, v64
	v_mad_u32_u24 v64, v64, s77, v73
	s_add_i32 s0, s0, s40
	s_lshl_b32 s41, s79, 4
	ds_write_b128 v64, v[56:59]
	ds_write_b128 v64, v[60:63] offset:64
	ds_write_b128 v64, v[48:51] offset:128
	ds_write_b128 v64, v[52:55] offset:192
	s_mul_hi_i32 s40, s0, 0x600
	s_mulk_i32 s0, 0x600
	s_and_b32 s41, s41, 0xffffff80
	v_ashrrev_i32_e32 v71, 3, v66
	s_nop 1
	ds_write_b128 v64, v[40:43] offset:4352
	ds_write_b128 v64, v[44:47] offset:4416
	ds_write_b128 v64, v[32:35] offset:4480
	ds_write_b128 v64, v[36:39] offset:4544
	v_mov_b32_e32 v64, s0
	v_mov_b32_e32 v65, s40
	s_movk_i32 s0, 0x600
	s_add_i32 s60, s41, 0xffffea00
	v_mad_i64_i32 v[64:65], s[40:41], v71, s0, v[64:65]
	v_and_b32_e32 v77, 7, v66
	s_nop 1
	v_lshl_or_b32 v64, v77, 4, v64
	v_lshl_add_u64 v[64:65], s[60:61], 1, v[64:65]
	v_mul_lo_u32 v71, v71, s77
	v_lshlrev_b32_e32 v77, 5, v77
	v_lshl_add_u64 v[66:67], s[10:11], 0, v[64:65]
	v_add3_u32 v71, v71, v77, s73
	s_mov_b32 s0, 0

.LBB0_1398:
	s_and_b64 vcc, exec, s[40:41]
	s_cbranch_vccz .LBB0_1403
	v_mov_b32_e32 v66, v188
	s_nop 1
	s_lshl_b32 s0, s79, 3
	v_and_b32_e32 v65, -16, v66
	v_and_b32_e32 v64, 15, v66
	v_add_u32_e32 v73, s78, v65
	v_mul_u32_u24_e32 v75, 0x110, v64
	v_mad_u32_u24 v64, v64, s77, v73
	ds_write_b128 v64, v[56:59]
	ds_write_b128 v64, v[60:63] offset:64
	ds_write_b128 v64, v[48:51] offset:128
	ds_write_b128 v64, v[52:55] offset:192
	s_nop 1
	ds_write_b128 v64, v[40:43] offset:4352
	ds_write_b128 v64, v[44:47] offset:4416
	ds_write_b128 v64, v[32:35] offset:4480
	ds_write_b128 v64, v[36:39] offset:4544
	s_and_b32 s0, s0, 0xf00
	v_ashrrev_i32_e32 v71, 3, v66
	s_nop 1
	v_mov_b32_e32 v80, s0
	s_movk_i32 s0, 0x600
	v_mad_i64_i32 v[64:65], s[40:41], v71, s0, v[80:81]
	v_and_b32_e32 v77, 7, v66
	v_lshl_or_b32 v64, v77, 4, v64
	v_mul_lo_u32 v71, v71, s77
	v_lshlrev_b32_e32 v77, 5, v77
	v_lshl_add_u64 v[66:67], s[18:19], 0, v[64:65]
	v_add3_u32 v71, v71, v77, s73
	s_mov_b32 s0, 0

.LBB0_1411:
	v_and_b32_e32 v60, -16, v109
	v_or_b32_e32 v63, 16, v80
	v_add_u32_e32 v62, s78, v60
	v_or_b32_e32 v60, v63, v206
	v_lshlrev_b32_e32 v60, 2, v60
	ds_bpermute_b32 v60, v60, v106
	v_mad_u32_u24 v61, v80, s77, v62
	ds_write_b128 v61, v[64:67]
	ds_write_b128 v61, v[56:59] offset:64
	ds_write_b128 v61, v[48:51] offset:128
	ds_write_b128 v61, v[52:55] offset:192
	s_waitcnt lgkmcnt(0)
	v_pk_mul_f32 v[50:51], v[42:43], v[60:61] op_sel_hi:[1,0]
	v_pk_mul_f32 v[42:43], v[46:47], v[60:61] op_sel_hi:[1,0]
	v_cvt_f32_ubyte0_e32 v46, v63
	v_pk_mul_f32 v[48:49], v[40:41], v[60:61] op_sel_hi:[1,0]
	v_pk_mul_f32 v[40:41], v[44:45], v[60:61] op_sel_hi:[1,0]
	v_mul_f32_e32 v45, v77, v46
	v_sin_f32_e32 v47, v45
	v_mul_f32_e32 v44, v75, v46
	v_sin_f32_e32 v52, v44
	v_cos_f32_e32 v44, v44
	v_cndmask_b32_e64 v53, -v47, v47, s[42:43]
	v_mul_f32_e32 v47, v108, v46
	v_mul_f32_e32 v46, v107, v46
	v_sin_f32_e32 v55, v47
	v_cos_f32_e32 v54, v47
	v_sin_f32_e32 v47, v46
	v_cos_f32_e32 v45, v45
	v_cos_f32_e32 v46, v46
	s_nop 1
	v_cndmask_b32_e64 v52, -v52, v52, s[42:43]
	v_cndmask_b32_e64 v55, -v55, v55, s[42:43]
	s_and_b64 vcc, exec, s[40:41]
	v_cndmask_b32_e64 v47, -v47, v47, s[42:43]
	s_cbranch_vccnz .LBB0_1414
	s_ashr_i32 s0, s44, 5
	s_mul_hi_i32 s45, s0, 0x55555556
	s_lshr_b32 s46, s45, 31
	s_add_i32 s45, s45, s46
	s_mul_i32 s45, s45, 3
	s_sub_i32 s0, s0, s45
	s_cmp_lg_u32 s0, 2
	s_cbranch_scc1 .LBB0_1414
	ds_bpermute_b32 v56, v219, v48
	ds_bpermute_b32 v57, v219, v49
	ds_bpermute_b32 v65, v219, v51
	ds_bpermute_b32 v91, v219, v43
	ds_bpermute_b32 v58, v219, v40
	ds_bpermute_b32 v59, v219, v41
	ds_bpermute_b32 v61, v219, v50
	ds_bpermute_b32 v63, v219, v42
	s_waitcnt lgkmcnt(0)
	v_pk_mul_f32 v[56:57], v[86:87], v[56:57]
	v_mov_b32_e32 v64, v51
	v_mov_b32_e32 v90, v43
	v_pk_mul_f32 v[64:65], v[84:85], v[64:65]
	v_pk_fma_f32 v[48:49], v[82:83], v[48:49], v[56:57]
	v_pk_mul_f32 v[56:57], v[46:47], v[90:91]
	v_pk_mul_f32 v[58:59], v[52:53], v[58:59]
	v_mul_f32_e32 v50, v71, v50
	v_mul_f32_e32 v66, v73, v61
	v_mul_f32_e32 v42, v54, v42
	v_mul_f32_e32 v88, v55, v63
	v_mov_b32_e32 v51, v64
	v_mov_b32_e32 v67, v65
	v_mov_b32_e32 v43, v56
	v_mov_b32_e32 v89, v57
	v_pk_add_f32 v[50:51], v[50:51], v[66:67]
	v_pk_fma_f32 v[40:41], v[44:45], v[40:41], v[58:59]
	v_pk_add_f32 v[42:43], v[42:43], v[88:89]

.LBB0_1417:
	v_mul_u32_u24_e32 v44, 0x110, v80
	v_ashrrev_i32_e32 v45, 3, v109
	v_add_u32_e32 v44, v44, v62
	s_movk_i32 s0, 0x480
	ds_write_b128 v44, v[48:51] offset:4352
	ds_write_b128 v44, v[40:43] offset:4416
	ds_write_b128 v44, v[32:35] offset:4480
	ds_write_b128 v44, v[36:39] offset:4544
	v_mad_i64_i32 v[32:33], s[46:47], v45, s0, 0
	v_and_b32_e32 v34, 7, v109
	s_ashr_i32 s45, s44, 31
	s_nop 1
	v_lshl_or_b32 v32, v34, 4, v32
	v_lshl_add_u64 v[36:37], s[44:45], 1, v[32:33]
	v_mul_lo_u32 v35, v45, s77
	v_lshlrev_b32_e32 v34, 5, v34
	v_lshl_add_u64 v[32:33], s[28:29], 0, v[36:37]
	v_add3_u32 v42, v35, v34, s73
	s_mov_b32 s0, 0
